# first adaLN norm: all modulation-table loads of a row issued up front; mLSTM gate loop: B-fragment loads batched per 512-wide K block
# speedup vs baseline: 1.0211x; 1.0122x over previous
; __device__ __forceinline__ unsigned cvt_pk_bf16(float lo, float hi) { const bf16x2_t r = __builtin_convertvector((f32x2){lo, hi}, bf16x2_t); return __builtin_bit_cast(unsigned, r); }
; __device__ __forceinline__ f32x4 ld_fx4(const unsigned long long* p) {
;     const long long a = (long long)p[0], b = (long long)p[1], c = (long long)p[2], d = (long long)p[3];
;     return (f32x4){(float)a, (float)b, (float)c, (float)d} * 9.094947017729282e-13f;
; }
; template <bool FINAL>
; __device__ __forceinline__ void norm_phase(const float* X, const float* mod, bf16_t* H, const float* fg, float* OUT, const unsigned long long* acc64 = nullptr, float* modf = nullptr) {
;     ...
;     for (int r = gw; r < MTOK; r += NGW) {
;         const f32x4* xr = (const f32x4*)(X + (size_t)r * DM) + lane;
;         f32x4 v[8]; float ss = 0.f;
; #pragma unroll
;         for (int j = 0; j < 8; ++j) { v[j] = xr[64 * j]; ss += (v[j][0] * v[j][0] + v[j][1] * v[j][1]) + (v[j][2] * v[j][2] + v[j][3] * v[j][3]); }
;         const float rstd = rsqrtf(wave_sum(ss) * (1.0f / DM) + EPS);
;         if (FINAL) {
; #pragma unroll
;             for (int j = 0; j < 8; ++j) { const f32x4 g = *((const f32x4*)fg + lane + 64 * j); *((f32x4*)(OUT + (size_t)r * DM) + lane + 64 * j) = v[j] * rstd * g; }
;         } else {
;             const float* mb = mod + (r >> 12) * 6144; const unsigned long long* mb64 = acc64 + (r >> 12) * 6144;
; #pragma unroll
;             for (int j = 0; j < 8; ++j) { const f32x4 sh = acc64 ? ld_fx4(mb64 + 4 * (lane + 64 * j)) : *((const f32x4*)mb + lane + 64 * j), sc = acc64 ? ld_fx4(mb64 + DM + 4 * (lane + 64 * j)) : *((const f32x4*)(mb + DM) + lane + 64 * j);
;                 const f32x4 o = v[j] * rstd * (sc + 1.0f) + sh; u32x2 w; w.x = cvt_pk_bf16(o[0], o[1]); w.y = cvt_pk_bf16(o[2], o[3]);
;                 *((u32x2*)(H + (size_t)r * DM) + lane + 64 * j) = w; }
.LBB0_121:
	v_ashrrev_i32_e32 v40, 12, v32
	v_mul_i32_i24_e32 v40, 0x1800, v40
	v_ashrrev_i32_e32 v41, 31, v40
	v_add_u32_e32 v32, s4, v32
	v_lshl_add_u64 v[40:41], v[40:41], 3, s[6:7]
	global_load_dwordx4 v[4:7], v[36:37], off offset:-4096
	global_load_dwordx4 v[0:3], v[36:37], off offset:-3072
	global_load_dwordx4 v[8:11], v[36:37], off offset:-2048
	global_load_dwordx4 v[12:15], v[36:37], off
	global_load_dwordx4 v[16:19], v[36:37], off offset:1024
	global_load_dwordx4 v[20:23], v[36:37], off offset:-1024
	global_load_dwordx4 v[24:27], v[36:37], off offset:3072
	global_load_dwordx4 v[28:31], v[36:37], off offset:2048
	v_cmp_lt_i32_e32 vcc, s46, v32
	v_lshl_add_u64 v[98:99], v[40:41], 0, v[34:35]
	s_or_b64 s[12:13], vcc, s[12:13]
	global_load_dwordx4 v[82:85], v[98:99], off offset:16
	global_load_dwordx4 v[86:89], v[98:99], off
	v_add_co_u32_e32 v64, vcc, s33, v98
	v_lshl_add_u64 v[100:101], v[98:99], 0, s[14:15]
	s_nop 0
	v_addc_co_u32_e32 v65, vcc, 0, v99, vcc
	global_load_dwordx4 v[90:93], v[64:65], off offset:-4096
	global_load_dwordx4 v[94:97], v[100:101], off offset:16
	v_add_co_u32_e32 v66, vcc, s17, v98
	v_lshl_add_u64 v[72:73], v[98:99], 0, s[2:3]
	s_nop 0
	v_addc_co_u32_e32 v67, vcc, 0, v99, vcc
	v_add_co_u32_e32 v52, vcc, s42, v98
	v_lshl_add_u64 v[74:75], v[98:99], 0, s[18:19]
	s_nop 0
	v_addc_co_u32_e32 v53, vcc, 0, v99, vcc
	v_add_co_u32_e32 v54, vcc, s43, v98
	v_lshl_add_u64 v[70:71], v[98:99], 0, s[20:21]
	s_nop 0
	v_addc_co_u32_e32 v55, vcc, 0, v99, vcc
	v_add_co_u32_e32 v40, vcc, s45, v98
	v_lshl_add_u64 v[68:69], v[98:99], 0, s[22:23]
	s_nop 0
	v_addc_co_u32_e32 v41, vcc, 0, v99, vcc
	v_add_co_u32_e32 v42, vcc, s44, v98
	v_lshl_add_u64 v[62:63], v[98:99], 0, s[24:25]
	s_nop 0
	v_addc_co_u32_e32 v43, vcc, 0, v99, vcc
	v_lshl_add_u64 v[60:61], v[98:99], 0, s[26:27]
	v_lshl_add_u64 v[58:59], v[98:99], 0, s[28:29]
	v_lshl_add_u64 v[56:57], v[98:99], 0, s[30:31]
	v_lshl_add_u64 v[48:49], v[98:99], 0, s[34:35]
	v_lshl_add_u64 v[50:51], v[98:99], 0, s[36:37]
	v_lshl_add_u64 v[46:47], v[98:99], 0, s[38:39]
	v_lshl_add_u64 v[44:45], v[98:99], 0, s[40:41]
	v_lshl_add_u64 v[36:37], v[36:37], 0, s[8:9]
	global_load_dwordx4 v[136:139], v[98:99], off offset:2048
	global_load_dwordx4 v[140:143], v[98:99], off offset:2064
	global_load_dwordx4 v[144:147], v[100:101], off offset:2048
	global_load_dwordx4 v[148:151], v[100:101], off offset:2064
	global_load_dwordx4 v[152:155], v[52:53], off offset:-4096
	global_load_dwordx4 v[156:159], v[72:73], off offset:16
	global_load_dwordx4 v[160:163], v[64:65], off
	global_load_dwordx4 v[164:167], v[74:75], off offset:16
	global_load_dwordx4 v[168:171], v[66:67], off offset:2048
	global_load_dwordx4 v[172:175], v[70:71], off offset:16
	global_load_dwordx4 v[176:179], v[64:65], off offset:2048
	global_load_dwordx4 v[180:183], v[68:69], off offset:16
	global_load_dwordx4 v[184:187], v[52:53], off
	global_load_dwordx4 v[188:191], v[62:63], off offset:16
	global_load_dwordx4 v[196:199], v[40:41], off offset:-4096
	global_load_dwordx4 v[202:205], v[60:61], off offset:16
	global_load_dwordx4 v[206:209], v[52:53], off offset:2048
	global_load_dwordx4 v[210:213], v[58:59], off offset:16
	global_load_dwordx4 v[214:217], v[54:55], off offset:2048
	global_load_dwordx4 v[218:221], v[56:57], off offset:16
	global_load_dwordx4 v[222:225], v[42:43], off
	global_load_dwordx4 v[226:229], v[48:49], off offset:16
	global_load_dwordx4 v[230:233], v[40:41], off
	global_load_dwordx4 v[234:237], v[50:51], off offset:16
	global_load_dwordx4 v[238:241], v[42:43], off offset:2048
	global_load_dwordx4 v[242:245], v[46:47], off offset:16
	global_load_dwordx4 v[246:249], v[40:41], off offset:2048
	global_load_dwordx4 v[250:253], v[44:45], off offset:16
	s_waitcnt vmcnt(39)
	v_mov_b32_e32 v104, v5
	s_waitcnt vmcnt(38)
	v_mov_b32_e32 v105, v1
	v_mov_b32_e32 v108, v7
	v_mov_b32_e32 v109, v3
	v_mov_b32_e32 v102, v4
	v_mov_b32_e32 v103, v0
	v_mov_b32_e32 v106, v6
	v_mov_b32_e32 v107, v2
	s_waitcnt vmcnt(37)
	v_pk_mul_f32 v[110:111], v[10:11], v[10:11]
	v_pk_mul_f32 v[112:113], v[8:9], v[8:9]
	v_pk_mul_f32 v[104:105], v[104:105], v[104:105]
	v_pk_mul_f32 v[108:109], v[108:109], v[108:109]
	v_pk_mov_b32 v[126:127], v[112:113], v[110:111] op_sel:[1,0]
	v_mov_b32_e32 v113, v111
	v_pk_fma_f32 v[102:103], v[102:103], v[102:103], v[104:105]
	v_pk_fma_f32 v[104:105], v[106:107], v[106:107], v[108:109]
	s_waitcnt vmcnt(35)
	v_pk_mul_f32 v[114:115], v[18:19], v[18:19]
	v_pk_mul_f32 v[116:117], v[16:17], v[16:17]
	s_waitcnt vmcnt(34)
	v_mul_f32_e32 v118, v21, v21
	v_mul_f32_e32 v120, v23, v23
	v_pk_add_f32 v[106:107], v[126:127], v[112:113]
	v_pk_add_f32 v[102:103], v[102:103], v[104:105]
	v_mul_f32_e32 v125, v12, v12
	v_mul_f32_e32 v128, v13, v13
	v_mul_f32_e32 v129, v14, v14
	v_mul_f32_e32 v130, v15, v15
	v_pk_mov_b32 v[110:111], v[116:117], v[114:115] op_sel:[1,0]
	v_mov_b32_e32 v117, v115
	v_pk_fma_f32 v[114:115], v[20:21], v[20:21], v[118:119] op_sel_hi:[1,1,0]
	v_pk_fma_f32 v[118:119], v[22:23], v[22:23], v[120:121] op_sel_hi:[1,1,0]
	v_pk_add_f32 v[104:105], v[106:107], v[106:107] op_sel:[0,1] op_sel_hi:[1,0]
	v_pk_add_f32 v[102:103], v[102:103], v[102:103] op_sel:[0,1] op_sel_hi:[1,0]
	s_waitcnt vmcnt(32)
	v_mul_f32_e32 v122, v29, v29
	v_mul_f32_e32 v124, v31, v31
	v_mov_b32_e32 v115, v129
	v_mov_b32_e32 v119, v130
	v_mov_b32_e32 v105, v128
	v_mov_b32_e32 v103, v125
	v_mul_f32_e32 v133, v26, v26
	v_mul_f32_e32 v134, v27, v27
	v_pk_fma_f32 v[120:121], v[28:29], v[28:29], v[122:123] op_sel_hi:[1,1,0]
	v_pk_fma_f32 v[122:123], v[30:31], v[30:31], v[124:125] op_sel_hi:[1,1,0]
	v_pk_add_f32 v[108:109], v[110:111], v[116:117]
	v_pk_add_f32 v[106:107], v[114:115], v[118:119]
	s_waitcnt vmcnt(30)
; __device__ __forceinline__ unsigned cvt_pk_bf16(float lo, float hi) { const bf16x2_t r = __builtin_convertvector((f32x2){lo, hi}, bf16x2_t); return __builtin_bit_cast(unsigned, r); }
; __device__ __forceinline__ f32x4 ld_fx4(const unsigned long long* p) {
;     const long long a = (long long)p[0], b = (long long)p[1], c = (long long)p[2], d = (long long)p[3];
;     return (f32x4){(float)a, (float)b, (float)c, (float)d} * 9.094947017729282e-13f;
; }
; template <bool FINAL>
; __device__ __forceinline__ void norm_phase(const float* X, const float* mod, bf16_t* H, const float* fg, float* OUT, const unsigned long long* acc64 = nullptr, float* modf = nullptr) {
;     ...
;     for (int r = gw; r < MTOK; r += NGW) {
;         const f32x4* xr = (const f32x4*)(X + (size_t)r * DM) + lane;
;         f32x4 v[8]; float ss = 0.f;
; #pragma unroll
;         for (int j = 0; j < 8; ++j) { v[j] = xr[64 * j]; ss += (v[j][0] * v[j][0] + v[j][1] * v[j][1]) + (v[j][2] * v[j][2] + v[j][3] * v[j][3]); }
;         const float rstd = rsqrtf(wave_sum(ss) * (1.0f / DM) + EPS);
;         if (FINAL) {
; #pragma unroll
;             for (int j = 0; j < 8; ++j) { const f32x4 g = *((const f32x4*)fg + lane + 64 * j); *((f32x4*)(OUT + (size_t)r * DM) + lane + 64 * j) = v[j] * rstd * g; }
;         } else {
;             const float* mb = mod + (r >> 12) * 6144; const unsigned long long* mb64 = acc64 + (r >> 12) * 6144;
; #pragma unroll
;             for (int j = 0; j < 8; ++j) { const f32x4 sh = acc64 ? ld_fx4(mb64 + 4 * (lane + 64 * j)) : *((const f32x4*)mb + lane + 64 * j), sc = acc64 ? ld_fx4(mb64 + DM + 4 * (lane + 64 * j)) : *((const f32x4*)(mb + DM) + lane + 64 * j);
;                 const f32x4 o = v[j] * rstd * (sc + 1.0f) + sh; u32x2 w; w.x = cvt_pk_bf16(o[0], o[1]); w.y = cvt_pk_bf16(o[2], o[3]);
;                 *((u32x2*)(H + (size_t)r * DM) + lane + 64 * j) = w; }
	v_xor_b32_e32 v112, v86, v87
	v_xor_b32_e32 v114, v88, v89
	v_xor_b32_e32 v116, v82, v83
	v_xor_b32_e32 v118, v84, v85
	v_pk_add_f32 v[102:103], v[102:103], v[104:105]
	v_mov_b32_e32 v121, v133
	v_mov_b32_e32 v123, v134
	v_ffbh_i32_e32 v113, v87
	v_ffbh_i32_e32 v115, v89
	v_ffbh_i32_e32 v117, v83
	v_ffbh_i32_e32 v119, v85
	v_ashrrev_i32_e32 v104, 31, v112
	v_ashrrev_i32_e32 v112, 31, v114
	v_ashrrev_i32_e32 v114, 31, v116
	v_ashrrev_i32_e32 v116, 31, v118
	s_waitcnt vmcnt(29)
	v_xor_b32_e32 v118, v90, v91
	v_pk_add_f32 v[102:103], v[102:103], v[106:107]
	v_mul_f32_e32 v131, v24, v24
	v_mul_f32_e32 v132, v25, v25
	v_pk_add_f32 v[108:109], v[108:109], v[108:109] op_sel:[0,1] op_sel_hi:[1,0]
	v_pk_add_f32 v[110:111], v[120:121], v[122:123]
	v_add_u32_e32 v105, -1, v113
	v_add_u32_e32 v113, -1, v115
	v_add_u32_e32 v115, -1, v117
	v_add_u32_e32 v117, -1, v119
	v_ffbh_i32_e32 v119, v91
	v_xor_b32_e32 v120, v92, v93
	v_add_u32_e32 v104, 32, v104
	v_add_u32_e32 v106, 32, v112
	v_add_u32_e32 v107, 32, v114
	v_add_u32_e32 v112, 32, v116
	v_ashrrev_i32_e32 v114, 31, v118
	v_pk_add_f32 v[102:103], v[102:103], v[102:103] op_sel:[0,1] op_sel_hi:[1,0]
	v_mov_b32_e32 v109, v132
	v_ffbh_i32_e32 v121, v93
	v_add_u32_e32 v116, -1, v119
	v_ashrrev_i32_e32 v118, 31, v120
	v_min_u32_e32 v104, v105, v104
	v_min_u32_e32 v105, v113, v106
	v_min_u32_e32 v106, v115, v107
	v_min_u32_e32 v107, v117, v112
	v_add_u32_e32 v112, 32, v114
	v_mov_b32_e32 v103, v131
	v_add_u32_e32 v119, -1, v121
	v_add_u32_e32 v113, 32, v118
	v_lshlrev_b64 v[82:83], v106, v[82:83]
	v_lshlrev_b64 v[84:85], v107, v[84:85]
	v_min_u32_e32 v112, v116, v112
	v_pk_add_f32 v[102:103], v[102:103], v[108:109]
	v_min_u32_e32 v113, v119, v113
	v_min_u32_e32 v82, 1, v82
	v_min_u32_e32 v84, 1, v84
	v_lshlrev_b64 v[90:91], v112, v[90:91]
	v_pk_add_f32 v[102:103], v[102:103], v[110:111]
	v_lshlrev_b64 v[92:93], v113, v[92:93]
	v_or_b32_e32 v82, v83, v82
	v_or_b32_e32 v83, v85, v84
	v_min_u32_e32 v84, 1, v90
	v_add_f32_e32 v90, v102, v103
	v_min_u32_e32 v85, 1, v92
	v_cvt_f32_i32_e32 v92, v82
	v_or_b32_e32 v82, v91, v84
	ds_bpermute_b32 v91, v76, v90
	s_waitcnt vmcnt(28)
	v_xor_b32_e32 v122, v94, v95
	v_xor_b32_e32 v124, v96, v97
	v_ffbh_i32_e32 v123, v95
	v_ffbh_i32_e32 v125, v97
	s_waitcnt lgkmcnt(0)
	v_add_f32_e32 v90, v90, v91
	ds_bpermute_b32 v91, v77, v90
	v_ashrrev_i32_e32 v120, 31, v122
	v_ashrrev_i32_e32 v122, 31, v124
	v_add_u32_e32 v121, -1, v123
	v_add_u32_e32 v123, -1, v125
	s_waitcnt lgkmcnt(0)
	v_add_f32_e32 v90, v90, v91
	ds_bpermute_b32 v91, v78, v90
	v_add_u32_e32 v114, 32, v120
	v_add_u32_e32 v115, 32, v122
	v_lshlrev_b64 v[86:87], v104, v[86:87]
	v_lshlrev_b64 v[88:89], v105, v[88:89]
	s_waitcnt lgkmcnt(0)
	v_add_f32_e32 v90, v90, v91
	ds_bpermute_b32 v91, v79, v90
	v_min_u32_e32 v114, v121, v114
	v_min_u32_e32 v115, v123, v115
	v_min_u32_e32 v86, 1, v86
	v_min_u32_e32 v88, 1, v88
	s_waitcnt lgkmcnt(0)
	v_add_f32_e32 v90, v90, v91
	ds_bpermute_b32 v91, v80, v90
	v_lshlrev_b64 v[94:95], v114, v[94:95]
	v_lshlrev_b64 v[96:97], v115, v[96:97]
	v_or_b32_e32 v86, v87, v86
	v_or_b32_e32 v87, v89, v88
	s_waitcnt lgkmcnt(0)
	v_add_f32_e32 v90, v90, v91
	ds_bpermute_b32 v91, v81, v90
	v_min_u32_e32 v88, 1, v94
	v_min_u32_e32 v89, 1, v96
	v_cvt_f32_i32_e32 v94, v83
	v_or_b32_e32 v83, v93, v85
	s_waitcnt lgkmcnt(0)
	v_add_f32_e32 v90, v90, v91
	v_fmamk_f32 v90, v90, 0x3a000000, v33
	v_mul_f32_e32 v91, 0x4b800000, v90
	v_cmp_gt_f32_e32 vcc, s5, v90
	v_or_b32_e32 v84, v95, v88
	v_or_b32_e32 v85, v97, v89
	v_cndmask_b32_e32 v90, v90, v91, vcc
	v_rsq_f32_e32 v90, v90
	v_cvt_f32_i32_e32 v86, v86
	v_cvt_f32_i32_e32 v87, v87
	v_cvt_f32_i32_e32 v88, v82
	v_cvt_f32_i32_e32 v89, v83
	v_cvt_f32_i32_e32 v93, v84
	v_cvt_f32_i32_e32 v95, v85
	v_sub_u32_e32 v104, 32, v104
	v_sub_u32_e32 v105, 32, v105
	v_sub_u32_e32 v108, 32, v112
	v_sub_u32_e32 v109, 32, v113
	v_sub_u32_e32 v112, 32, v114
	v_sub_u32_e32 v113, 32, v115
	v_mul_f32_e32 v91, 0x45800000, v90
	v_sub_u32_e32 v106, 32, v106
	v_sub_u32_e32 v107, 32, v107
	v_ldexp_f32 v82, v86, v104
	v_ldexp_f32 v83, v87, v105
	v_ldexp_f32 v86, v88, v108
	v_ldexp_f32 v87, v89, v109
	v_ldexp_f32 v88, v93, v112
	v_ldexp_f32 v89, v95, v113
	v_cndmask_b32_e32 v90, v90, v91, vcc
	v_ldexp_f32 v84, v92, v106
	v_ldexp_f32 v85, v94, v107
	v_pk_fma_f32 v[86:87], v[86:87], s[16:17], 1.0 op_sel_hi:[1,0,0]
	v_pk_fma_f32 v[88:89], v[88:89], s[16:17], 1.0 op_sel_hi:[1,0,0]
	v_pk_mul_f32 v[92:93], v[6:7], v[90:91] op_sel_hi:[1,0]
	v_pk_mul_f32 v[94:95], v[4:5], v[90:91] op_sel_hi:[1,0]
	v_pk_mul_f32 v[104:105], v[10:11], v[90:91] op_sel_hi:[1,0]
	v_pk_mul_f32 v[106:107], v[8:9], v[90:91] op_sel_hi:[1,0]
	v_pk_mul_f32 v[8:9], v[18:19], v[90:91] op_sel_hi:[1,0]
	v_pk_mul_f32 v[10:11], v[16:17], v[90:91] op_sel_hi:[1,0]
	v_pk_mul_f32 v[16:17], v[86:87], v[94:95]
	v_pk_mul_f32 v[18:19], v[88:89], v[92:93]
	v_pk_fma_f32 v[16:17], v[82:83], s[16:17], v[16:17] op_sel_hi:[1,0,1]
	v_pk_fma_f32 v[18:19], v[84:85], s[16:17], v[18:19] op_sel_hi:[1,0,1]
	v_cvt_pk_bf16_f32 v16, v16, v17
	v_cvt_pk_bf16_f32 v17, v18, v19
	global_store_dwordx2 v[38:39], v[16:17], off
	v_pk_mul_f32 v[96:97], v[2:3], v[90:91] op_sel_hi:[1,0]
	v_pk_mul_f32 v[102:103], v[0:1], v[90:91] op_sel_hi:[1,0]
	v_pk_mul_f32 v[4:5], v[30:31], v[90:91] op_sel_hi:[1,0]
	v_pk_mul_f32 v[6:7], v[28:29], v[90:91] op_sel_hi:[1,0]
	v_pk_mul_f32 v[0:1], v[26:27], v[90:91] op_sel_hi:[1,0]
	v_pk_mul_f32 v[2:3], v[24:25], v[90:91] op_sel_hi:[1,0]
	s_waitcnt vmcnt(25)
; __device__ __forceinline__ unsigned cvt_pk_bf16(float lo, float hi) { const bf16x2_t r = __builtin_convertvector((f32x2){lo, hi}, bf16x2_t); return __builtin_bit_cast(unsigned, r); }
; __device__ __forceinline__ f32x4 ld_fx4(const unsigned long long* p) {
;     const long long a = (long long)p[0], b = (long long)p[1], c = (long long)p[2], d = (long long)p[3];
;     return (f32x4){(float)a, (float)b, (float)c, (float)d} * 9.094947017729282e-13f;
; }
; template <bool FINAL>
; __device__ __forceinline__ void norm_phase(const float* X, const float* mod, bf16_t* H, const float* fg, float* OUT, const unsigned long long* acc64 = nullptr, float* modf = nullptr) {
;     ...
;     for (int r = gw; r < MTOK; r += NGW) {
;         const f32x4* xr = (const f32x4*)(X + (size_t)r * DM) + lane;
;         f32x4 v[8]; float ss = 0.f;
; #pragma unroll
;         for (int j = 0; j < 8; ++j) { v[j] = xr[64 * j]; ss += (v[j][0] * v[j][0] + v[j][1] * v[j][1]) + (v[j][2] * v[j][2] + v[j][3] * v[j][3]); }
;         const float rstd = rsqrtf(wave_sum(ss) * (1.0f / DM) + EPS);
;         if (FINAL) {
; #pragma unroll
;             for (int j = 0; j < 8; ++j) { const f32x4 g = *((const f32x4*)fg + lane + 64 * j); *((f32x4*)(OUT + (size_t)r * DM) + lane + 64 * j) = v[j] * rstd * g; }
;         } else {
;             const float* mb = mod + (r >> 12) * 6144; const unsigned long long* mb64 = acc64 + (r >> 12) * 6144;
; #pragma unroll
;             for (int j = 0; j < 8; ++j) { const f32x4 sh = acc64 ? ld_fx4(mb64 + 4 * (lane + 64 * j)) : *((const f32x4*)mb + lane + 64 * j), sc = acc64 ? ld_fx4(mb64 + DM + 4 * (lane + 64 * j)) : *((const f32x4*)(mb + DM) + lane + 64 * j);
;                 const f32x4 o = v[j] * rstd * (sc + 1.0f) + sh; u32x2 w; w.x = cvt_pk_bf16(o[0], o[1]); w.y = cvt_pk_bf16(o[2], o[3]);
;                 *((u32x2*)(H + (size_t)r * DM) + lane + 64 * j) = w; }
	v_mov_b32_e32 v16, v136
	v_mov_b32_e32 v17, v137
	v_mov_b32_e32 v18, v138
	v_mov_b32_e32 v19, v139
	v_mov_b32_e32 v24, v140
	v_mov_b32_e32 v25, v141
	v_mov_b32_e32 v26, v142
	v_mov_b32_e32 v27, v143
	v_mov_b32_e32 v28, v144
	v_mov_b32_e32 v29, v145
	v_mov_b32_e32 v30, v146
	v_mov_b32_e32 v31, v147
	v_mov_b32_e32 v82, v148
	v_mov_b32_e32 v83, v149
	v_mov_b32_e32 v84, v150
	v_mov_b32_e32 v85, v151
	v_pk_mul_f32 v[22:23], v[22:23], v[90:91] op_sel_hi:[1,0]
	v_pk_mul_f32 v[20:21], v[20:21], v[90:91] op_sel_hi:[1,0]
	v_pk_mul_f32 v[14:15], v[14:15], v[90:91] op_sel_hi:[1,0]
	v_pk_mul_f32 v[12:13], v[12:13], v[90:91] op_sel_hi:[1,0]
	v_xor_b32_e32 v86, v16, v17
	v_xor_b32_e32 v88, v18, v19
	v_xor_b32_e32 v90, v24, v25
	v_xor_b32_e32 v92, v26, v27
	v_xor_b32_e32 v94, v28, v29
	v_xor_b32_e32 v98, v30, v31
	v_xor_b32_e32 v100, v82, v83
	v_xor_b32_e32 v108, v84, v85
	v_ffbh_i32_e32 v87, v17
	v_ffbh_i32_e32 v89, v19
	v_ffbh_i32_e32 v91, v25
	v_ffbh_i32_e32 v93, v27
	v_ffbh_i32_e32 v95, v29
	v_ffbh_i32_e32 v99, v31
	v_ffbh_i32_e32 v101, v83
	v_ffbh_i32_e32 v109, v85
	v_ashrrev_i32_e32 v86, 31, v86
	v_ashrrev_i32_e32 v88, 31, v88
	v_ashrrev_i32_e32 v90, 31, v90
	v_ashrrev_i32_e32 v92, 31, v92
	v_ashrrev_i32_e32 v94, 31, v94
	v_ashrrev_i32_e32 v98, 31, v98
	v_ashrrev_i32_e32 v100, 31, v100
	v_ashrrev_i32_e32 v108, 31, v108
	v_add_u32_e32 v87, -1, v87
	v_add_u32_e32 v89, -1, v89
	v_add_u32_e32 v91, -1, v91
	v_add_u32_e32 v93, -1, v93
	v_add_u32_e32 v95, -1, v95
	v_add_u32_e32 v99, -1, v99
	v_add_u32_e32 v101, -1, v101
	v_add_u32_e32 v109, -1, v109
	v_add_u32_e32 v86, 32, v86
	v_add_u32_e32 v88, 32, v88
	v_add_u32_e32 v90, 32, v90
	v_add_u32_e32 v92, 32, v92
	v_add_u32_e32 v94, 32, v94
	v_add_u32_e32 v98, 32, v98
	v_add_u32_e32 v100, 32, v100
	v_add_u32_e32 v108, 32, v108
	v_min_u32_e32 v86, v87, v86
	v_min_u32_e32 v87, v89, v88
	v_min_u32_e32 v88, v91, v90
	v_min_u32_e32 v89, v93, v92
	v_min_u32_e32 v90, v95, v94
	v_min_u32_e32 v91, v99, v98
	v_min_u32_e32 v92, v101, v100
	v_min_u32_e32 v93, v109, v108
	v_lshlrev_b64 v[16:17], v86, v[16:17]
	v_lshlrev_b64 v[18:19], v87, v[18:19]
	v_lshlrev_b64 v[24:25], v88, v[24:25]
	v_lshlrev_b64 v[26:27], v89, v[26:27]
	v_lshlrev_b64 v[28:29], v90, v[28:29]
	v_lshlrev_b64 v[30:31], v91, v[30:31]
	v_lshlrev_b64 v[82:83], v92, v[82:83]
	v_lshlrev_b64 v[84:85], v93, v[84:85]
	v_min_u32_e32 v16, 1, v16
	v_min_u32_e32 v18, 1, v18
	v_min_u32_e32 v24, 1, v24
	v_min_u32_e32 v26, 1, v26
	v_min_u32_e32 v28, 1, v28
	v_min_u32_e32 v30, 1, v30
	v_min_u32_e32 v82, 1, v82
	v_min_u32_e32 v84, 1, v84
	v_or_b32_e32 v16, v17, v16
	v_or_b32_e32 v17, v19, v18
	v_or_b32_e32 v18, v25, v24
	v_or_b32_e32 v19, v27, v26
	v_or_b32_e32 v24, v29, v28
	v_or_b32_e32 v25, v31, v30
	v_or_b32_e32 v26, v83, v82
	v_or_b32_e32 v27, v85, v84
	v_cvt_f32_i32_e32 v24, v24
	v_cvt_f32_i32_e32 v25, v25
	v_cvt_f32_i32_e32 v26, v26
	v_cvt_f32_i32_e32 v27, v27
	v_cvt_f32_i32_e32 v16, v16
	v_cvt_f32_i32_e32 v17, v17
	v_cvt_f32_i32_e32 v18, v18
	v_cvt_f32_i32_e32 v19, v19
	v_sub_u32_e32 v90, 32, v90
	v_sub_u32_e32 v91, 32, v91
	v_sub_u32_e32 v92, 32, v92
	v_sub_u32_e32 v93, 32, v93
	v_ldexp_f32 v24, v24, v90
	v_ldexp_f32 v25, v25, v91
	v_ldexp_f32 v26, v26, v92
	v_ldexp_f32 v27, v27, v93
	v_sub_u32_e32 v86, 32, v86
	v_sub_u32_e32 v87, 32, v87
	v_sub_u32_e32 v88, 32, v88
	v_sub_u32_e32 v89, 32, v89
	v_pk_fma_f32 v[26:27], v[26:27], s[16:17], 1.0 op_sel_hi:[1,0,0]
	v_pk_fma_f32 v[24:25], v[24:25], s[16:17], 1.0 op_sel_hi:[1,0,0]
	v_ldexp_f32 v16, v16, v86
	v_ldexp_f32 v17, v17, v87
	v_ldexp_f32 v18, v18, v88
	v_ldexp_f32 v19, v19, v89
	v_pk_mul_f32 v[24:25], v[102:103], v[24:25]
	v_pk_mul_f32 v[26:27], v[96:97], v[26:27]
	v_pk_fma_f32 v[16:17], v[16:17], s[16:17], v[24:25] op_sel_hi:[1,0,1]
	v_pk_fma_f32 v[18:19], v[18:19], s[16:17], v[26:27] op_sel_hi:[1,0,1]
	v_cvt_pk_bf16_f32 v16, v16, v17
	v_cvt_pk_bf16_f32 v17, v18, v19
	global_store_dwordx2 v[38:39], v[16:17], off offset:512
	s_waitcnt vmcnt(22)
	v_mov_b32_e32 v16, v152
	v_mov_b32_e32 v17, v153
	v_mov_b32_e32 v18, v154
	v_mov_b32_e32 v19, v155
	v_mov_b32_e32 v24, v156
	v_mov_b32_e32 v25, v157
	v_mov_b32_e32 v26, v158
	v_mov_b32_e32 v27, v159
	v_mov_b32_e32 v28, v160
	v_mov_b32_e32 v29, v161
	v_mov_b32_e32 v30, v162
	v_mov_b32_e32 v31, v163
	v_mov_b32_e32 v72, v164
	v_mov_b32_e32 v73, v165
	v_mov_b32_e32 v74, v166
	v_mov_b32_e32 v75, v167
	v_xor_b32_e32 v82, v16, v17
	v_xor_b32_e32 v84, v18, v19
	v_xor_b32_e32 v86, v24, v25
	v_xor_b32_e32 v88, v26, v27
	v_xor_b32_e32 v90, v28, v29
	v_xor_b32_e32 v92, v30, v31
	v_xor_b32_e32 v94, v72, v73
	v_xor_b32_e32 v96, v74, v75
	v_ffbh_i32_e32 v83, v17
	v_ffbh_i32_e32 v85, v19
	v_ffbh_i32_e32 v87, v25
	v_ffbh_i32_e32 v89, v27
	v_ffbh_i32_e32 v91, v29
	v_ffbh_i32_e32 v93, v31
	v_ffbh_i32_e32 v95, v73
	v_ffbh_i32_e32 v97, v75
	v_ashrrev_i32_e32 v82, 31, v82
	v_ashrrev_i32_e32 v84, 31, v84
	v_ashrrev_i32_e32 v86, 31, v86
	v_ashrrev_i32_e32 v88, 31, v88
	v_ashrrev_i32_e32 v90, 31, v90
	v_ashrrev_i32_e32 v92, 31, v92
	v_ashrrev_i32_e32 v94, 31, v94
	v_ashrrev_i32_e32 v96, 31, v96
	v_add_u32_e32 v83, -1, v83
	v_add_u32_e32 v85, -1, v85
	v_add_u32_e32 v87, -1, v87
	v_add_u32_e32 v89, -1, v89
	v_add_u32_e32 v91, -1, v91
	v_add_u32_e32 v93, -1, v93
	v_add_u32_e32 v95, -1, v95
	v_add_u32_e32 v97, -1, v97
	v_add_u32_e32 v82, 32, v82
	v_add_u32_e32 v84, 32, v84
	v_add_u32_e32 v86, 32, v86
	v_add_u32_e32 v88, 32, v88
	v_add_u32_e32 v90, 32, v90
	v_add_u32_e32 v92, 32, v92
	v_add_u32_e32 v94, 32, v94
	v_add_u32_e32 v96, 32, v96
	v_min_u32_e32 v82, v83, v82
	v_min_u32_e32 v83, v85, v84
	v_min_u32_e32 v84, v87, v86
	v_min_u32_e32 v85, v89, v88
	v_min_u32_e32 v86, v91, v90
; __device__ __forceinline__ unsigned cvt_pk_bf16(float lo, float hi) { const bf16x2_t r = __builtin_convertvector((f32x2){lo, hi}, bf16x2_t); return __builtin_bit_cast(unsigned, r); }
; __device__ __forceinline__ f32x4 ld_fx4(const unsigned long long* p) {
;     const long long a = (long long)p[0], b = (long long)p[1], c = (long long)p[2], d = (long long)p[3];
;     return (f32x4){(float)a, (float)b, (float)c, (float)d} * 9.094947017729282e-13f;
; }
; template <bool FINAL>
; __device__ __forceinline__ void norm_phase(const float* X, const float* mod, bf16_t* H, const float* fg, float* OUT, const unsigned long long* acc64 = nullptr, float* modf = nullptr) {
;     ...
;     for (int r = gw; r < MTOK; r += NGW) {
;         const f32x4* xr = (const f32x4*)(X + (size_t)r * DM) + lane;
;         f32x4 v[8]; float ss = 0.f;
; #pragma unroll
;         for (int j = 0; j < 8; ++j) { v[j] = xr[64 * j]; ss += (v[j][0] * v[j][0] + v[j][1] * v[j][1]) + (v[j][2] * v[j][2] + v[j][3] * v[j][3]); }
;         const float rstd = rsqrtf(wave_sum(ss) * (1.0f / DM) + EPS);
;         if (FINAL) {
; #pragma unroll
;             for (int j = 0; j < 8; ++j) { const f32x4 g = *((const f32x4*)fg + lane + 64 * j); *((f32x4*)(OUT + (size_t)r * DM) + lane + 64 * j) = v[j] * rstd * g; }
;         } else {
;             const float* mb = mod + (r >> 12) * 6144; const unsigned long long* mb64 = acc64 + (r >> 12) * 6144;
; #pragma unroll
;             for (int j = 0; j < 8; ++j) { const f32x4 sh = acc64 ? ld_fx4(mb64 + 4 * (lane + 64 * j)) : *((const f32x4*)mb + lane + 64 * j), sc = acc64 ? ld_fx4(mb64 + DM + 4 * (lane + 64 * j)) : *((const f32x4*)(mb + DM) + lane + 64 * j);
;                 const f32x4 o = v[j] * rstd * (sc + 1.0f) + sh; u32x2 w; w.x = cvt_pk_bf16(o[0], o[1]); w.y = cvt_pk_bf16(o[2], o[3]);
;                 *((u32x2*)(H + (size_t)r * DM) + lane + 64 * j) = w; }
	v_min_u32_e32 v87, v93, v92
	v_min_u32_e32 v88, v95, v94
	v_min_u32_e32 v89, v97, v96
	v_lshlrev_b64 v[16:17], v82, v[16:17]
	v_lshlrev_b64 v[18:19], v83, v[18:19]
	v_lshlrev_b64 v[24:25], v84, v[24:25]
	v_lshlrev_b64 v[26:27], v85, v[26:27]
	v_lshlrev_b64 v[28:29], v86, v[28:29]
	v_lshlrev_b64 v[30:31], v87, v[30:31]
	v_lshlrev_b64 v[72:73], v88, v[72:73]
	v_lshlrev_b64 v[74:75], v89, v[74:75]
	v_min_u32_e32 v16, 1, v16
	v_min_u32_e32 v18, 1, v18
	v_min_u32_e32 v24, 1, v24
	v_min_u32_e32 v26, 1, v26
	v_min_u32_e32 v28, 1, v28
	v_min_u32_e32 v30, 1, v30
	v_min_u32_e32 v72, 1, v72
	v_min_u32_e32 v74, 1, v74
	v_or_b32_e32 v16, v17, v16
	v_or_b32_e32 v17, v19, v18
	v_or_b32_e32 v18, v25, v24
	v_or_b32_e32 v19, v27, v26
	v_or_b32_e32 v24, v29, v28
	v_or_b32_e32 v25, v31, v30
	v_or_b32_e32 v26, v73, v72
	v_or_b32_e32 v27, v75, v74
	v_cvt_f32_i32_e32 v24, v24
	v_cvt_f32_i32_e32 v25, v25
	v_cvt_f32_i32_e32 v26, v26
	v_cvt_f32_i32_e32 v27, v27
	v_cvt_f32_i32_e32 v16, v16
	v_cvt_f32_i32_e32 v17, v17
	v_cvt_f32_i32_e32 v18, v18
	v_cvt_f32_i32_e32 v19, v19
	v_sub_u32_e32 v86, 32, v86
	v_sub_u32_e32 v87, 32, v87
	v_sub_u32_e32 v88, 32, v88
	v_sub_u32_e32 v89, 32, v89
	v_ldexp_f32 v24, v24, v86
	v_ldexp_f32 v25, v25, v87
	v_ldexp_f32 v26, v26, v88
	v_ldexp_f32 v27, v27, v89
	v_sub_u32_e32 v82, 32, v82
	v_sub_u32_e32 v83, 32, v83
	v_sub_u32_e32 v84, 32, v84
	v_sub_u32_e32 v85, 32, v85
	v_pk_fma_f32 v[24:25], v[24:25], s[16:17], 1.0 op_sel_hi:[1,0,0]
	v_pk_fma_f32 v[26:27], v[26:27], s[16:17], 1.0 op_sel_hi:[1,0,0]
	v_ldexp_f32 v16, v16, v82
	v_ldexp_f32 v17, v17, v83
	v_ldexp_f32 v18, v18, v84
	v_ldexp_f32 v19, v19, v85
	v_pk_mul_f32 v[24:25], v[106:107], v[24:25]
	v_pk_mul_f32 v[26:27], v[104:105], v[26:27]
	v_pk_fma_f32 v[16:17], v[16:17], s[16:17], v[24:25] op_sel_hi:[1,0,1]
	v_pk_fma_f32 v[18:19], v[18:19], s[16:17], v[26:27] op_sel_hi:[1,0,1]
	v_cvt_pk_bf16_f32 v16, v16, v17
	v_cvt_pk_bf16_f32 v17, v18, v19
	global_store_dwordx2 v[38:39], v[16:17], off offset:1024
	s_waitcnt vmcnt(19)
	v_mov_b32_e32 v16, v168
	v_mov_b32_e32 v17, v169
	v_mov_b32_e32 v18, v170
	v_mov_b32_e32 v19, v171
	v_mov_b32_e32 v24, v172
	v_mov_b32_e32 v25, v173
	v_mov_b32_e32 v26, v174
	v_mov_b32_e32 v27, v175
	v_mov_b32_e32 v28, v176
	v_mov_b32_e32 v29, v177
	v_mov_b32_e32 v30, v178
	v_mov_b32_e32 v31, v179
	v_mov_b32_e32 v64, v180
	v_mov_b32_e32 v65, v181
	v_mov_b32_e32 v66, v182
	v_mov_b32_e32 v67, v183
	v_xor_b32_e32 v68, v16, v17
	v_xor_b32_e32 v70, v18, v19
	v_xor_b32_e32 v72, v24, v25
	v_xor_b32_e32 v74, v26, v27
	v_xor_b32_e32 v82, v28, v29
	v_xor_b32_e32 v84, v30, v31
	v_xor_b32_e32 v86, v64, v65
	v_xor_b32_e32 v88, v66, v67
	v_ffbh_i32_e32 v69, v17
	v_ffbh_i32_e32 v71, v19
	v_ffbh_i32_e32 v73, v25
	v_ffbh_i32_e32 v75, v27
	v_ffbh_i32_e32 v83, v29
	v_ffbh_i32_e32 v85, v31
	v_ffbh_i32_e32 v87, v65
	v_ffbh_i32_e32 v89, v67
	v_ashrrev_i32_e32 v68, 31, v68
	v_ashrrev_i32_e32 v70, 31, v70
	v_ashrrev_i32_e32 v72, 31, v72
	v_ashrrev_i32_e32 v74, 31, v74
	v_ashrrev_i32_e32 v82, 31, v82
	v_ashrrev_i32_e32 v84, 31, v84
	v_ashrrev_i32_e32 v86, 31, v86
	v_ashrrev_i32_e32 v88, 31, v88
	v_add_u32_e32 v69, -1, v69
	v_add_u32_e32 v71, -1, v71
	v_add_u32_e32 v73, -1, v73
	v_add_u32_e32 v75, -1, v75
	v_add_u32_e32 v83, -1, v83
	v_add_u32_e32 v85, -1, v85
	v_add_u32_e32 v87, -1, v87
	v_add_u32_e32 v89, -1, v89
	v_add_u32_e32 v68, 32, v68
	v_add_u32_e32 v70, 32, v70
	v_add_u32_e32 v72, 32, v72
	v_add_u32_e32 v74, 32, v74
	v_add_u32_e32 v82, 32, v82
	v_add_u32_e32 v84, 32, v84
	v_add_u32_e32 v86, 32, v86
	v_add_u32_e32 v88, 32, v88
	v_min_u32_e32 v68, v69, v68
	v_min_u32_e32 v69, v71, v70
	v_min_u32_e32 v70, v73, v72
	v_min_u32_e32 v71, v75, v74
	v_min_u32_e32 v72, v83, v82
	v_min_u32_e32 v73, v85, v84
	v_min_u32_e32 v74, v87, v86
	v_min_u32_e32 v75, v89, v88
	v_lshlrev_b64 v[16:17], v68, v[16:17]
	v_lshlrev_b64 v[18:19], v69, v[18:19]
	v_lshlrev_b64 v[24:25], v70, v[24:25]
	v_lshlrev_b64 v[26:27], v71, v[26:27]
	v_lshlrev_b64 v[28:29], v72, v[28:29]
	v_lshlrev_b64 v[30:31], v73, v[30:31]
	v_lshlrev_b64 v[64:65], v74, v[64:65]
	v_lshlrev_b64 v[66:67], v75, v[66:67]
	v_min_u32_e32 v16, 1, v16
	v_min_u32_e32 v18, 1, v18
	v_min_u32_e32 v24, 1, v24
	v_min_u32_e32 v26, 1, v26
	v_min_u32_e32 v28, 1, v28
	v_min_u32_e32 v30, 1, v30
	v_min_u32_e32 v64, 1, v64
	v_min_u32_e32 v66, 1, v66
	v_or_b32_e32 v16, v17, v16
	v_or_b32_e32 v17, v19, v18
	v_or_b32_e32 v18, v25, v24
	v_or_b32_e32 v19, v27, v26
	v_or_b32_e32 v24, v29, v28
	v_or_b32_e32 v25, v31, v30
	v_or_b32_e32 v26, v65, v64
	v_or_b32_e32 v27, v67, v66
	v_cvt_f32_i32_e32 v24, v24
	v_cvt_f32_i32_e32 v25, v25
	v_cvt_f32_i32_e32 v26, v26
	v_cvt_f32_i32_e32 v27, v27
	v_cvt_f32_i32_e32 v16, v16
	v_cvt_f32_i32_e32 v17, v17
	v_cvt_f32_i32_e32 v18, v18
	v_cvt_f32_i32_e32 v19, v19
	v_sub_u32_e32 v72, 32, v72
	v_sub_u32_e32 v73, 32, v73
	v_sub_u32_e32 v74, 32, v74
	v_sub_u32_e32 v75, 32, v75
	v_ldexp_f32 v24, v24, v72
	v_ldexp_f32 v25, v25, v73
	v_ldexp_f32 v26, v26, v74
	v_ldexp_f32 v27, v27, v75
	v_sub_u32_e32 v68, 32, v68
	v_sub_u32_e32 v69, 32, v69
	v_sub_u32_e32 v70, 32, v70
	v_sub_u32_e32 v71, 32, v71
	v_pk_fma_f32 v[24:25], v[24:25], s[16:17], 1.0 op_sel_hi:[1,0,0]
	v_pk_fma_f32 v[26:27], v[26:27], s[16:17], 1.0 op_sel_hi:[1,0,0]
	v_ldexp_f32 v16, v16, v68
	v_ldexp_f32 v17, v17, v69
	v_ldexp_f32 v18, v18, v70
	v_ldexp_f32 v19, v19, v71
	v_pk_mul_f32 v[20:21], v[20:21], v[24:25]
	v_pk_mul_f32 v[22:23], v[22:23], v[26:27]
	v_pk_fma_f32 v[16:17], v[16:17], s[16:17], v[20:21] op_sel_hi:[1,0,1]
	v_pk_fma_f32 v[18:19], v[18:19], s[16:17], v[22:23] op_sel_hi:[1,0,1]
	v_cvt_pk_bf16_f32 v16, v16, v17
	v_cvt_pk_bf16_f32 v17, v18, v19
	global_store_dwordx2 v[38:39], v[16:17], off offset:1536
	s_waitcnt vmcnt(16)
; __device__ __forceinline__ unsigned cvt_pk_bf16(float lo, float hi) { const bf16x2_t r = __builtin_convertvector((f32x2){lo, hi}, bf16x2_t); return __builtin_bit_cast(unsigned, r); }
; __device__ __forceinline__ f32x4 ld_fx4(const unsigned long long* p) {
;     const long long a = (long long)p[0], b = (long long)p[1], c = (long long)p[2], d = (long long)p[3];
;     return (f32x4){(float)a, (float)b, (float)c, (float)d} * 9.094947017729282e-13f;
; }
; template <bool FINAL>
; __device__ __forceinline__ void norm_phase(const float* X, const float* mod, bf16_t* H, const float* fg, float* OUT, const unsigned long long* acc64 = nullptr, float* modf = nullptr) {
;     ...
;     for (int r = gw; r < MTOK; r += NGW) {
;         const f32x4* xr = (const f32x4*)(X + (size_t)r * DM) + lane;
;         f32x4 v[8]; float ss = 0.f;
; #pragma unroll
;         for (int j = 0; j < 8; ++j) { v[j] = xr[64 * j]; ss += (v[j][0] * v[j][0] + v[j][1] * v[j][1]) + (v[j][2] * v[j][2] + v[j][3] * v[j][3]); }
;         const float rstd = rsqrtf(wave_sum(ss) * (1.0f / DM) + EPS);
;         if (FINAL) {
; #pragma unroll
;             for (int j = 0; j < 8; ++j) { const f32x4 g = *((const f32x4*)fg + lane + 64 * j); *((f32x4*)(OUT + (size_t)r * DM) + lane + 64 * j) = v[j] * rstd * g; }
;         } else {
;             const float* mb = mod + (r >> 12) * 6144; const unsigned long long* mb64 = acc64 + (r >> 12) * 6144;
; #pragma unroll
;             for (int j = 0; j < 8; ++j) { const f32x4 sh = acc64 ? ld_fx4(mb64 + 4 * (lane + 64 * j)) : *((const f32x4*)mb + lane + 64 * j), sc = acc64 ? ld_fx4(mb64 + DM + 4 * (lane + 64 * j)) : *((const f32x4*)(mb + DM) + lane + 64 * j);
;                 const f32x4 o = v[j] * rstd * (sc + 1.0f) + sh; u32x2 w; w.x = cvt_pk_bf16(o[0], o[1]); w.y = cvt_pk_bf16(o[2], o[3]);
;                 *((u32x2*)(H + (size_t)r * DM) + lane + 64 * j) = w; }
	v_mov_b32_e32 v16, v184
	v_mov_b32_e32 v17, v185
	v_mov_b32_e32 v18, v186
	v_mov_b32_e32 v19, v187
	v_mov_b32_e32 v20, v188
	v_mov_b32_e32 v21, v189
	v_mov_b32_e32 v22, v190
	v_mov_b32_e32 v23, v191
	v_mov_b32_e32 v24, v196
	v_mov_b32_e32 v25, v197
	v_mov_b32_e32 v26, v198
	v_mov_b32_e32 v27, v199
	v_mov_b32_e32 v28, v202
	v_mov_b32_e32 v29, v203
	v_mov_b32_e32 v30, v204
	v_mov_b32_e32 v31, v205
	v_xor_b32_e32 v60, v16, v17
	v_xor_b32_e32 v62, v18, v19
	v_xor_b32_e32 v64, v20, v21
	v_xor_b32_e32 v66, v22, v23
	v_xor_b32_e32 v68, v24, v25
	v_xor_b32_e32 v70, v26, v27
	v_xor_b32_e32 v72, v28, v29
	v_xor_b32_e32 v74, v30, v31
	v_ffbh_i32_e32 v61, v17
	v_ffbh_i32_e32 v63, v19
	v_ffbh_i32_e32 v65, v21
	v_ffbh_i32_e32 v67, v23
	v_ffbh_i32_e32 v69, v25
	v_ffbh_i32_e32 v71, v27
	v_ffbh_i32_e32 v73, v29
	v_ffbh_i32_e32 v75, v31
	v_ashrrev_i32_e32 v60, 31, v60
	v_ashrrev_i32_e32 v62, 31, v62
	v_ashrrev_i32_e32 v64, 31, v64
	v_ashrrev_i32_e32 v66, 31, v66
	v_ashrrev_i32_e32 v68, 31, v68
	v_ashrrev_i32_e32 v70, 31, v70
	v_ashrrev_i32_e32 v72, 31, v72
	v_ashrrev_i32_e32 v74, 31, v74
	v_add_u32_e32 v61, -1, v61
	v_add_u32_e32 v63, -1, v63
	v_add_u32_e32 v65, -1, v65
	v_add_u32_e32 v67, -1, v67
	v_add_u32_e32 v69, -1, v69
	v_add_u32_e32 v71, -1, v71
	v_add_u32_e32 v73, -1, v73
	v_add_u32_e32 v75, -1, v75
	v_add_u32_e32 v60, 32, v60
	v_add_u32_e32 v62, 32, v62
	v_add_u32_e32 v64, 32, v64
	v_add_u32_e32 v66, 32, v66
	v_add_u32_e32 v68, 32, v68
	v_add_u32_e32 v70, 32, v70
	v_add_u32_e32 v72, 32, v72
	v_add_u32_e32 v74, 32, v74
	v_min_u32_e32 v60, v61, v60
	v_min_u32_e32 v61, v63, v62
	v_min_u32_e32 v62, v65, v64
	v_min_u32_e32 v63, v67, v66
	v_min_u32_e32 v64, v69, v68
	v_min_u32_e32 v65, v71, v70
	v_min_u32_e32 v66, v73, v72
	v_min_u32_e32 v67, v75, v74
	v_lshlrev_b64 v[16:17], v60, v[16:17]
	v_lshlrev_b64 v[18:19], v61, v[18:19]
	v_lshlrev_b64 v[20:21], v62, v[20:21]
	v_lshlrev_b64 v[22:23], v63, v[22:23]
	v_lshlrev_b64 v[24:25], v64, v[24:25]
	v_lshlrev_b64 v[26:27], v65, v[26:27]
	v_lshlrev_b64 v[28:29], v66, v[28:29]
	v_lshlrev_b64 v[30:31], v67, v[30:31]
	v_min_u32_e32 v16, 1, v16
	v_min_u32_e32 v18, 1, v18
	v_min_u32_e32 v20, 1, v20
	v_min_u32_e32 v22, 1, v22
	v_min_u32_e32 v24, 1, v24
	v_min_u32_e32 v26, 1, v26
	v_min_u32_e32 v28, 1, v28
	v_min_u32_e32 v30, 1, v30
	v_or_b32_e32 v16, v17, v16
	v_or_b32_e32 v17, v19, v18
	v_or_b32_e32 v18, v21, v20
	v_or_b32_e32 v19, v23, v22
	v_or_b32_e32 v20, v25, v24
	v_or_b32_e32 v21, v27, v26
	v_or_b32_e32 v22, v29, v28
	v_or_b32_e32 v23, v31, v30
	v_cvt_f32_i32_e32 v20, v20
	v_cvt_f32_i32_e32 v21, v21
	v_cvt_f32_i32_e32 v22, v22
	v_cvt_f32_i32_e32 v23, v23
	v_cvt_f32_i32_e32 v16, v16
	v_cvt_f32_i32_e32 v17, v17
	v_cvt_f32_i32_e32 v18, v18
	v_cvt_f32_i32_e32 v19, v19
	v_sub_u32_e32 v64, 32, v64
	v_sub_u32_e32 v65, 32, v65
	v_sub_u32_e32 v66, 32, v66
	v_sub_u32_e32 v67, 32, v67
	v_ldexp_f32 v20, v20, v64
	v_ldexp_f32 v21, v21, v65
	v_ldexp_f32 v22, v22, v66
	v_ldexp_f32 v23, v23, v67
	v_sub_u32_e32 v60, 32, v60
	v_sub_u32_e32 v61, 32, v61
	v_sub_u32_e32 v62, 32, v62
	v_sub_u32_e32 v63, 32, v63
	v_pk_fma_f32 v[20:21], v[20:21], s[16:17], 1.0 op_sel_hi:[1,0,0]
	v_pk_fma_f32 v[22:23], v[22:23], s[16:17], 1.0 op_sel_hi:[1,0,0]
	v_ldexp_f32 v16, v16, v60
	v_ldexp_f32 v17, v17, v61
	v_ldexp_f32 v18, v18, v62
	v_ldexp_f32 v19, v19, v63
	v_pk_mul_f32 v[12:13], v[12:13], v[20:21]
	v_pk_mul_f32 v[14:15], v[14:15], v[22:23]
	v_pk_fma_f32 v[12:13], v[16:17], s[16:17], v[12:13] op_sel_hi:[1,0,1]
	v_pk_fma_f32 v[14:15], v[18:19], s[16:17], v[14:15] op_sel_hi:[1,0,1]
	v_cvt_pk_bf16_f32 v12, v12, v13
	v_cvt_pk_bf16_f32 v13, v14, v15
	global_store_dwordx2 v[38:39], v[12:13], off offset:2048
	s_waitcnt vmcnt(13)
	v_mov_b32_e32 v12, v206
	v_mov_b32_e32 v13, v207
	v_mov_b32_e32 v14, v208
	v_mov_b32_e32 v15, v209
	v_mov_b32_e32 v16, v210
	v_mov_b32_e32 v17, v211
	v_mov_b32_e32 v18, v212
	v_mov_b32_e32 v19, v213
	v_mov_b32_e32 v20, v214
	v_mov_b32_e32 v21, v215
	v_mov_b32_e32 v22, v216
	v_mov_b32_e32 v23, v217
	v_mov_b32_e32 v24, v218
	v_mov_b32_e32 v25, v219
	v_mov_b32_e32 v26, v220
	v_mov_b32_e32 v27, v221
	v_xor_b32_e32 v28, v12, v13
	v_xor_b32_e32 v30, v14, v15
	v_xor_b32_e32 v52, v16, v17
	v_xor_b32_e32 v54, v18, v19
	v_xor_b32_e32 v56, v20, v21
	v_xor_b32_e32 v58, v22, v23
	v_xor_b32_e32 v60, v24, v25
	v_xor_b32_e32 v62, v26, v27
	v_ffbh_i32_e32 v29, v13
	v_ffbh_i32_e32 v31, v15
	v_ffbh_i32_e32 v53, v17
	v_ffbh_i32_e32 v55, v19
	v_ffbh_i32_e32 v57, v21
	v_ffbh_i32_e32 v59, v23
	v_ffbh_i32_e32 v61, v25
	v_ffbh_i32_e32 v63, v27
	v_ashrrev_i32_e32 v28, 31, v28
	v_ashrrev_i32_e32 v30, 31, v30
	v_ashrrev_i32_e32 v52, 31, v52
	v_ashrrev_i32_e32 v54, 31, v54
	v_ashrrev_i32_e32 v56, 31, v56
	v_ashrrev_i32_e32 v58, 31, v58
	v_ashrrev_i32_e32 v60, 31, v60
	v_ashrrev_i32_e32 v62, 31, v62
	v_add_u32_e32 v29, -1, v29
	v_add_u32_e32 v31, -1, v31
	v_add_u32_e32 v53, -1, v53
	v_add_u32_e32 v55, -1, v55
	v_add_u32_e32 v57, -1, v57
	v_add_u32_e32 v59, -1, v59
	v_add_u32_e32 v61, -1, v61
	v_add_u32_e32 v63, -1, v63
	v_add_u32_e32 v28, 32, v28
	v_add_u32_e32 v30, 32, v30
	v_add_u32_e32 v52, 32, v52
	v_add_u32_e32 v54, 32, v54
	v_add_u32_e32 v56, 32, v56
	v_add_u32_e32 v58, 32, v58
	v_add_u32_e32 v60, 32, v60
	v_add_u32_e32 v62, 32, v62
	v_min_u32_e32 v28, v29, v28
	v_min_u32_e32 v29, v31, v30
	v_min_u32_e32 v30, v53, v52
	v_min_u32_e32 v31, v55, v54
	v_min_u32_e32 v52, v57, v56
	v_min_u32_e32 v53, v59, v58
	v_min_u32_e32 v54, v61, v60
	v_min_u32_e32 v55, v63, v62
	v_lshlrev_b64 v[12:13], v28, v[12:13]
	v_lshlrev_b64 v[14:15], v29, v[14:15]
	v_lshlrev_b64 v[16:17], v30, v[16:17]
	v_lshlrev_b64 v[18:19], v31, v[18:19]
	v_lshlrev_b64 v[20:21], v52, v[20:21]
; __device__ __forceinline__ unsigned cvt_pk_bf16(float lo, float hi) { const bf16x2_t r = __builtin_convertvector((f32x2){lo, hi}, bf16x2_t); return __builtin_bit_cast(unsigned, r); }
; __device__ __forceinline__ f32x4 ld_fx4(const unsigned long long* p) {
;     const long long a = (long long)p[0], b = (long long)p[1], c = (long long)p[2], d = (long long)p[3];
;     return (f32x4){(float)a, (float)b, (float)c, (float)d} * 9.094947017729282e-13f;
; }
; template <bool FINAL>
; __device__ __forceinline__ void norm_phase(const float* X, const float* mod, bf16_t* H, const float* fg, float* OUT, const unsigned long long* acc64 = nullptr, float* modf = nullptr) {
;     ...
;     for (int r = gw; r < MTOK; r += NGW) {
;         const f32x4* xr = (const f32x4*)(X + (size_t)r * DM) + lane;
;         f32x4 v[8]; float ss = 0.f;
; #pragma unroll
;         for (int j = 0; j < 8; ++j) { v[j] = xr[64 * j]; ss += (v[j][0] * v[j][0] + v[j][1] * v[j][1]) + (v[j][2] * v[j][2] + v[j][3] * v[j][3]); }
;         const float rstd = rsqrtf(wave_sum(ss) * (1.0f / DM) + EPS);
;         if (FINAL) {
; #pragma unroll
;             for (int j = 0; j < 8; ++j) { const f32x4 g = *((const f32x4*)fg + lane + 64 * j); *((f32x4*)(OUT + (size_t)r * DM) + lane + 64 * j) = v[j] * rstd * g; }
;         } else {
;             const float* mb = mod + (r >> 12) * 6144; const unsigned long long* mb64 = acc64 + (r >> 12) * 6144;
; #pragma unroll
;             for (int j = 0; j < 8; ++j) { const f32x4 sh = acc64 ? ld_fx4(mb64 + 4 * (lane + 64 * j)) : *((const f32x4*)mb + lane + 64 * j), sc = acc64 ? ld_fx4(mb64 + DM + 4 * (lane + 64 * j)) : *((const f32x4*)(mb + DM) + lane + 64 * j);
;                 const f32x4 o = v[j] * rstd * (sc + 1.0f) + sh; u32x2 w; w.x = cvt_pk_bf16(o[0], o[1]); w.y = cvt_pk_bf16(o[2], o[3]);
;                 *((u32x2*)(H + (size_t)r * DM) + lane + 64 * j) = w; }
	v_lshlrev_b64 v[22:23], v53, v[22:23]
	v_lshlrev_b64 v[24:25], v54, v[24:25]
	v_lshlrev_b64 v[26:27], v55, v[26:27]
	v_min_u32_e32 v12, 1, v12
	v_min_u32_e32 v14, 1, v14
	v_min_u32_e32 v16, 1, v16
	v_min_u32_e32 v18, 1, v18
	v_min_u32_e32 v20, 1, v20
	v_min_u32_e32 v22, 1, v22
	v_min_u32_e32 v24, 1, v24
	v_min_u32_e32 v26, 1, v26
	v_or_b32_e32 v12, v13, v12
	v_or_b32_e32 v13, v15, v14
	v_or_b32_e32 v14, v17, v16
	v_or_b32_e32 v15, v19, v18
	v_or_b32_e32 v16, v21, v20
	v_or_b32_e32 v17, v23, v22
	v_or_b32_e32 v18, v25, v24
	v_or_b32_e32 v19, v27, v26
	v_cvt_f32_i32_e32 v16, v16
	v_cvt_f32_i32_e32 v17, v17
	v_cvt_f32_i32_e32 v18, v18
	v_cvt_f32_i32_e32 v19, v19
	v_cvt_f32_i32_e32 v12, v12
	v_cvt_f32_i32_e32 v13, v13
	v_cvt_f32_i32_e32 v14, v14
	v_cvt_f32_i32_e32 v15, v15
	v_sub_u32_e32 v52, 32, v52
	v_sub_u32_e32 v53, 32, v53
	v_sub_u32_e32 v54, 32, v54
	v_sub_u32_e32 v55, 32, v55
	v_ldexp_f32 v16, v16, v52
	v_ldexp_f32 v17, v17, v53
	v_ldexp_f32 v18, v18, v54
	v_ldexp_f32 v19, v19, v55
	v_sub_u32_e32 v28, 32, v28
	v_sub_u32_e32 v29, 32, v29
	v_sub_u32_e32 v30, 32, v30
	v_sub_u32_e32 v31, 32, v31
	v_pk_fma_f32 v[16:17], v[16:17], s[16:17], 1.0 op_sel_hi:[1,0,0]
	v_pk_fma_f32 v[18:19], v[18:19], s[16:17], 1.0 op_sel_hi:[1,0,0]
	v_ldexp_f32 v12, v12, v28
	v_ldexp_f32 v13, v13, v29
	v_ldexp_f32 v14, v14, v30
	v_ldexp_f32 v15, v15, v31
	v_pk_mul_f32 v[10:11], v[10:11], v[16:17]
	v_pk_mul_f32 v[8:9], v[8:9], v[18:19]
	v_pk_fma_f32 v[10:11], v[12:13], s[16:17], v[10:11] op_sel_hi:[1,0,1]
	v_pk_fma_f32 v[8:9], v[14:15], s[16:17], v[8:9] op_sel_hi:[1,0,1]
	v_cvt_pk_bf16_f32 v10, v10, v11
	v_cvt_pk_bf16_f32 v11, v8, v9
	global_store_dwordx2 v[38:39], v[10:11], off offset:2560
	s_waitcnt vmcnt(10)
	v_mov_b32_e32 v8, v222
	v_mov_b32_e32 v9, v223
	v_mov_b32_e32 v10, v224
	v_mov_b32_e32 v11, v225
	v_mov_b32_e32 v12, v226
	v_mov_b32_e32 v13, v227
	v_mov_b32_e32 v14, v228
	v_mov_b32_e32 v15, v229
	v_mov_b32_e32 v16, v230
	v_mov_b32_e32 v17, v231
	v_mov_b32_e32 v18, v232
	v_mov_b32_e32 v19, v233
	v_mov_b32_e32 v20, v234
	v_mov_b32_e32 v21, v235
	v_mov_b32_e32 v22, v236
	v_mov_b32_e32 v23, v237
	v_xor_b32_e32 v24, v8, v9
	v_xor_b32_e32 v26, v10, v11
	v_xor_b32_e32 v28, v12, v13
	v_xor_b32_e32 v30, v14, v15
	v_xor_b32_e32 v48, v16, v17
	v_xor_b32_e32 v50, v18, v19
	v_xor_b32_e32 v52, v20, v21
	v_xor_b32_e32 v54, v22, v23
	v_ffbh_i32_e32 v25, v9
	v_ffbh_i32_e32 v27, v11
	v_ffbh_i32_e32 v29, v13
	v_ffbh_i32_e32 v31, v15
	v_ffbh_i32_e32 v49, v17
	v_ffbh_i32_e32 v51, v19
	v_ffbh_i32_e32 v53, v21
	v_ffbh_i32_e32 v55, v23
	v_ashrrev_i32_e32 v24, 31, v24
	v_ashrrev_i32_e32 v26, 31, v26
	v_ashrrev_i32_e32 v28, 31, v28
	v_ashrrev_i32_e32 v30, 31, v30
	v_ashrrev_i32_e32 v48, 31, v48
	v_ashrrev_i32_e32 v50, 31, v50
	v_ashrrev_i32_e32 v52, 31, v52
	v_ashrrev_i32_e32 v54, 31, v54
	v_add_u32_e32 v25, -1, v25
	v_add_u32_e32 v27, -1, v27
	v_add_u32_e32 v29, -1, v29
	v_add_u32_e32 v31, -1, v31
	v_add_u32_e32 v49, -1, v49
	v_add_u32_e32 v51, -1, v51
	v_add_u32_e32 v53, -1, v53
	v_add_u32_e32 v55, -1, v55
	v_add_u32_e32 v24, 32, v24
	v_add_u32_e32 v26, 32, v26
	v_add_u32_e32 v28, 32, v28
	v_add_u32_e32 v30, 32, v30
	v_add_u32_e32 v48, 32, v48
	v_add_u32_e32 v50, 32, v50
	v_add_u32_e32 v52, 32, v52
	v_add_u32_e32 v54, 32, v54
	v_min_u32_e32 v24, v25, v24
	v_min_u32_e32 v25, v27, v26
	v_min_u32_e32 v26, v29, v28
	v_min_u32_e32 v27, v31, v30
	v_min_u32_e32 v28, v49, v48
	v_min_u32_e32 v29, v51, v50
	v_min_u32_e32 v30, v53, v52
	v_min_u32_e32 v31, v55, v54
	v_lshlrev_b64 v[8:9], v24, v[8:9]
	v_lshlrev_b64 v[10:11], v25, v[10:11]
	v_lshlrev_b64 v[12:13], v26, v[12:13]
	v_lshlrev_b64 v[14:15], v27, v[14:15]
	v_lshlrev_b64 v[16:17], v28, v[16:17]
	v_lshlrev_b64 v[18:19], v29, v[18:19]
	v_lshlrev_b64 v[20:21], v30, v[20:21]
	v_lshlrev_b64 v[22:23], v31, v[22:23]
	v_min_u32_e32 v8, 1, v8
	v_min_u32_e32 v10, 1, v10
	v_min_u32_e32 v12, 1, v12
	v_min_u32_e32 v14, 1, v14
	v_min_u32_e32 v16, 1, v16
	v_min_u32_e32 v18, 1, v18
	v_min_u32_e32 v20, 1, v20
	v_min_u32_e32 v22, 1, v22
	v_or_b32_e32 v8, v9, v8
	v_or_b32_e32 v9, v11, v10
	v_or_b32_e32 v10, v13, v12
	v_or_b32_e32 v11, v15, v14
	v_or_b32_e32 v12, v17, v16
	v_or_b32_e32 v13, v19, v18
	v_or_b32_e32 v14, v21, v20
	v_or_b32_e32 v15, v23, v22
	v_cvt_f32_i32_e32 v12, v12
	v_cvt_f32_i32_e32 v13, v13
	v_cvt_f32_i32_e32 v14, v14
	v_cvt_f32_i32_e32 v15, v15
	v_cvt_f32_i32_e32 v8, v8
	v_cvt_f32_i32_e32 v9, v9
	v_cvt_f32_i32_e32 v10, v10
	v_cvt_f32_i32_e32 v11, v11
	v_sub_u32_e32 v28, 32, v28
	v_sub_u32_e32 v29, 32, v29
	v_sub_u32_e32 v30, 32, v30
	v_sub_u32_e32 v31, 32, v31
	v_ldexp_f32 v12, v12, v28
	v_ldexp_f32 v13, v13, v29
	v_ldexp_f32 v14, v14, v30
	v_ldexp_f32 v15, v15, v31
	v_sub_u32_e32 v24, 32, v24
	v_sub_u32_e32 v25, 32, v25
	v_sub_u32_e32 v26, 32, v26
	v_sub_u32_e32 v27, 32, v27
	v_pk_fma_f32 v[12:13], v[12:13], s[16:17], 1.0 op_sel_hi:[1,0,0]
	v_pk_fma_f32 v[14:15], v[14:15], s[16:17], 1.0 op_sel_hi:[1,0,0]
	v_ldexp_f32 v8, v8, v24
	v_ldexp_f32 v9, v9, v25
	v_ldexp_f32 v10, v10, v26
	v_ldexp_f32 v11, v11, v27
	v_pk_mul_f32 v[6:7], v[6:7], v[12:13]
	v_pk_mul_f32 v[4:5], v[4:5], v[14:15]
	v_pk_fma_f32 v[6:7], v[8:9], s[16:17], v[6:7] op_sel_hi:[1,0,1]
	v_pk_fma_f32 v[4:5], v[10:11], s[16:17], v[4:5] op_sel_hi:[1,0,1]
	v_cvt_pk_bf16_f32 v6, v6, v7
	v_cvt_pk_bf16_f32 v7, v4, v5
	global_store_dwordx2 v[38:39], v[6:7], off offset:3072
	s_waitcnt vmcnt(7)
; __device__ __forceinline__ unsigned cvt_pk_bf16(float lo, float hi) { const bf16x2_t r = __builtin_convertvector((f32x2){lo, hi}, bf16x2_t); return __builtin_bit_cast(unsigned, r); }
; __device__ __forceinline__ f32x4 ld_fx4(const unsigned long long* p) {
;     const long long a = (long long)p[0], b = (long long)p[1], c = (long long)p[2], d = (long long)p[3];
;     return (f32x4){(float)a, (float)b, (float)c, (float)d} * 9.094947017729282e-13f;
; }
; template <bool FINAL>
; __device__ __forceinline__ void norm_phase(const float* X, const float* mod, bf16_t* H, const float* fg, float* OUT, const unsigned long long* acc64 = nullptr, float* modf = nullptr) {
;     ...
;     for (int r = gw; r < MTOK; r += NGW) {
;         const f32x4* xr = (const f32x4*)(X + (size_t)r * DM) + lane;
;         f32x4 v[8]; float ss = 0.f;
; #pragma unroll
;         for (int j = 0; j < 8; ++j) { v[j] = xr[64 * j]; ss += (v[j][0] * v[j][0] + v[j][1] * v[j][1]) + (v[j][2] * v[j][2] + v[j][3] * v[j][3]); }
;         const float rstd = rsqrtf(wave_sum(ss) * (1.0f / DM) + EPS);
;         if (FINAL) {
; #pragma unroll
;             for (int j = 0; j < 8; ++j) { const f32x4 g = *((const f32x4*)fg + lane + 64 * j); *((f32x4*)(OUT + (size_t)r * DM) + lane + 64 * j) = v[j] * rstd * g; }
;         } else {
;             const float* mb = mod + (r >> 12) * 6144; const unsigned long long* mb64 = acc64 + (r >> 12) * 6144;
; #pragma unroll
;             for (int j = 0; j < 8; ++j) { const f32x4 sh = acc64 ? ld_fx4(mb64 + 4 * (lane + 64 * j)) : *((const f32x4*)mb + lane + 64 * j), sc = acc64 ? ld_fx4(mb64 + DM + 4 * (lane + 64 * j)) : *((const f32x4*)(mb + DM) + lane + 64 * j);
;                 const f32x4 o = v[j] * rstd * (sc + 1.0f) + sh; u32x2 w; w.x = cvt_pk_bf16(o[0], o[1]); w.y = cvt_pk_bf16(o[2], o[3]);
;                 *((u32x2*)(H + (size_t)r * DM) + lane + 64 * j) = w; }
	v_mov_b32_e32 v4, v238
	v_mov_b32_e32 v5, v239
	v_mov_b32_e32 v6, v240
	v_mov_b32_e32 v7, v241
	v_mov_b32_e32 v8, v242
	v_mov_b32_e32 v9, v243
	v_mov_b32_e32 v10, v244
	v_mov_b32_e32 v11, v245
	v_mov_b32_e32 v12, v246
	v_mov_b32_e32 v13, v247
	v_mov_b32_e32 v14, v248
	v_mov_b32_e32 v15, v249
	v_mov_b32_e32 v16, v250
	v_mov_b32_e32 v17, v251
	v_mov_b32_e32 v18, v252
	v_mov_b32_e32 v19, v253
	v_xor_b32_e32 v20, v4, v5
	v_xor_b32_e32 v22, v6, v7
	v_xor_b32_e32 v24, v8, v9
	v_xor_b32_e32 v26, v10, v11
	v_xor_b32_e32 v28, v12, v13
	v_xor_b32_e32 v30, v14, v15
	v_xor_b32_e32 v40, v16, v17
	v_xor_b32_e32 v42, v18, v19
	v_ffbh_i32_e32 v21, v5
	v_ffbh_i32_e32 v23, v7
	v_ffbh_i32_e32 v25, v9
	v_ffbh_i32_e32 v27, v11
	v_ffbh_i32_e32 v29, v13
	v_ffbh_i32_e32 v31, v15
	v_ffbh_i32_e32 v41, v17
	v_ffbh_i32_e32 v43, v19
	v_ashrrev_i32_e32 v20, 31, v20
	v_ashrrev_i32_e32 v22, 31, v22
	v_ashrrev_i32_e32 v24, 31, v24
	v_ashrrev_i32_e32 v26, 31, v26
	v_ashrrev_i32_e32 v28, 31, v28
	v_ashrrev_i32_e32 v30, 31, v30
	v_ashrrev_i32_e32 v40, 31, v40
	v_ashrrev_i32_e32 v42, 31, v42
	v_add_u32_e32 v21, -1, v21
	v_add_u32_e32 v23, -1, v23
	v_add_u32_e32 v25, -1, v25
	v_add_u32_e32 v27, -1, v27
	v_add_u32_e32 v29, -1, v29
	v_add_u32_e32 v31, -1, v31
	v_add_u32_e32 v41, -1, v41
	v_add_u32_e32 v43, -1, v43
	v_add_u32_e32 v20, 32, v20
	v_add_u32_e32 v22, 32, v22
	v_add_u32_e32 v24, 32, v24
	v_add_u32_e32 v26, 32, v26
	v_add_u32_e32 v28, 32, v28
	v_add_u32_e32 v30, 32, v30
	v_add_u32_e32 v40, 32, v40
	v_add_u32_e32 v42, 32, v42
	v_min_u32_e32 v20, v21, v20
	v_min_u32_e32 v21, v23, v22
	v_min_u32_e32 v22, v25, v24
	v_min_u32_e32 v23, v27, v26
	v_min_u32_e32 v24, v29, v28
	v_min_u32_e32 v25, v31, v30
	v_min_u32_e32 v26, v41, v40
	v_min_u32_e32 v27, v43, v42
	v_lshlrev_b64 v[4:5], v20, v[4:5]
	v_lshlrev_b64 v[6:7], v21, v[6:7]
	v_lshlrev_b64 v[8:9], v22, v[8:9]
	v_lshlrev_b64 v[10:11], v23, v[10:11]
	v_lshlrev_b64 v[12:13], v24, v[12:13]
	v_lshlrev_b64 v[14:15], v25, v[14:15]
	v_lshlrev_b64 v[16:17], v26, v[16:17]
	v_lshlrev_b64 v[18:19], v27, v[18:19]
	v_min_u32_e32 v4, 1, v4
	v_min_u32_e32 v6, 1, v6
	v_min_u32_e32 v8, 1, v8
	v_min_u32_e32 v10, 1, v10
	v_min_u32_e32 v12, 1, v12
	v_min_u32_e32 v14, 1, v14
	v_min_u32_e32 v16, 1, v16
	v_min_u32_e32 v18, 1, v18
	v_or_b32_e32 v4, v5, v4
	v_or_b32_e32 v5, v7, v6
	v_or_b32_e32 v6, v9, v8
	v_or_b32_e32 v7, v11, v10
	v_or_b32_e32 v8, v13, v12
	v_or_b32_e32 v9, v15, v14
	v_or_b32_e32 v10, v17, v16
	v_or_b32_e32 v11, v19, v18
	v_cvt_f32_i32_e32 v8, v8
	v_cvt_f32_i32_e32 v9, v9
	v_cvt_f32_i32_e32 v10, v10
	v_cvt_f32_i32_e32 v11, v11
	v_cvt_f32_i32_e32 v4, v4
	v_cvt_f32_i32_e32 v5, v5
	v_cvt_f32_i32_e32 v6, v6
	v_cvt_f32_i32_e32 v7, v7
	v_sub_u32_e32 v24, 32, v24
	v_sub_u32_e32 v25, 32, v25
	v_sub_u32_e32 v26, 32, v26
	v_sub_u32_e32 v27, 32, v27
	v_ldexp_f32 v8, v8, v24
	v_ldexp_f32 v9, v9, v25
	v_ldexp_f32 v10, v10, v26
	v_ldexp_f32 v11, v11, v27
	v_sub_u32_e32 v20, 32, v20
	v_sub_u32_e32 v21, 32, v21
	v_sub_u32_e32 v22, 32, v22
	v_sub_u32_e32 v23, 32, v23
	v_pk_fma_f32 v[8:9], v[8:9], s[16:17], 1.0 op_sel_hi:[1,0,0]
	v_pk_fma_f32 v[10:11], v[10:11], s[16:17], 1.0 op_sel_hi:[1,0,0]
	v_ldexp_f32 v4, v4, v20
	v_ldexp_f32 v5, v5, v21
	v_ldexp_f32 v6, v6, v22
	v_ldexp_f32 v7, v7, v23
	v_pk_mul_f32 v[2:3], v[2:3], v[8:9]
	v_pk_mul_f32 v[0:1], v[0:1], v[10:11]
	v_pk_fma_f32 v[2:3], v[4:5], s[16:17], v[2:3] op_sel_hi:[1,0,1]
	v_pk_fma_f32 v[0:1], v[6:7], s[16:17], v[0:1] op_sel_hi:[1,0,1]
	v_cvt_pk_bf16_f32 v2, v2, v3
	v_cvt_pk_bf16_f32 v3, v0, v1
	global_store_dwordx2 v[38:39], v[2:3], off offset:3584
	v_lshl_add_u64 v[38:39], v[38:39], 0, s[10:11]
	s_andn2_b64 exec, exec, s[12:13]
	s_cbranch_execnz .LBB0_121

; __device__ __forceinline__ float log_sigmoidf_(float x) { return fminf(x, 0.f) - log1pf(__expf(-fabsf(x))); }
; __device__ __forceinline__ void gates_phase(const bf16_t* HB, const bf16_t* WG16, const float* bg, float* LI, float* LF) {
;     ...
;         const bf16_t* ap = HB + (size_t)(rt * 16 + fr) * DM + 8 * fq; const bf16_t* bp = WG16 + fr * DM + 8 * fq;
;         f32x4 acc = {0.f, 0.f, 0.f, 0.f};
; #pragma unroll 16
;         for (int kk = 0; kk < 64; ++kk) { const bf16x8 a = *(const bf16x8*)(ap + 32 * kk), b = *(const bf16x8*)(bp + 32 * kk);
;             acc = __builtin_amdgcn_mfma_f32_16x16x32_bf16(a, b, acc, 0, 0, 0); }
;         const int r0 = rt * 16 + 4 * fq, bb = r0 >> 12, s = r0 & 4095, g = fr & 7;
;         const float bias = bg[fr];
;         f32x4 o;
;         if (fr < 8) { o = acc + bias; *(f32x4*)(LI + (size_t)(bb * 8 + g) * SEQ + s) = o; }
;         else {
; #pragma unroll
;             for (int j = 0; j < 4; ++j) o[j] = log_sigmoidf_(acc[j] + bias);
;             *(f32x4*)(LF + (size_t)(bb * 8 + g) * SEQ + s) = o; }
.LBB0_178:
	v_lshl_add_u64 v[6:7], v[4:5], 0, s[16:17]
	v_add_co_u32_e32 v6, vcc, 0x14500000, v6
	v_lshl_add_u64 v[22:23], v[16:17], 0, s[16:17]
	s_nop 0
	v_addc_co_u32_e32 v7, vcc, 0, v7, vcc
	v_add_co_u32_e32 v22, vcc, 0x134000, v22
	s_add_u32 s16, s16, 0x400
	s_nop 0
	v_addc_co_u32_e32 v23, vcc, 0, v23, vcc
	global_load_dwordx4 v[30:33], v[6:7], off
	global_load_dwordx4 v[34:37], v[6:7], off offset:64
	global_load_dwordx4 v[38:41], v[6:7], off offset:128
	global_load_dwordx4 v[42:45], v[6:7], off offset:192
	global_load_dwordx4 v[46:49], v[6:7], off offset:256
	global_load_dwordx4 v[50:53], v[6:7], off offset:320
	global_load_dwordx4 v[54:57], v[6:7], off offset:384
	global_load_dwordx4 v[58:61], v[6:7], off offset:448
	global_load_dwordx4 v[62:65], v[6:7], off offset:512
	global_load_dwordx4 v[66:69], v[6:7], off offset:576
	global_load_dwordx4 v[70:73], v[6:7], off offset:640
	global_load_dwordx4 v[74:77], v[6:7], off offset:704
	global_load_dwordx4 v[78:81], v[6:7], off offset:768
	global_load_dwordx4 v[82:85], v[6:7], off offset:832
	global_load_dwordx4 v[86:89], v[6:7], off offset:896
	global_load_dwordx4 v[90:93], v[6:7], off offset:960
	global_load_dwordx4 v[96:99], v[22:23], off
	global_load_dwordx4 v[100:103], v[22:23], off offset:64
	global_load_dwordx4 v[104:107], v[22:23], off offset:128
	global_load_dwordx4 v[108:111], v[22:23], off offset:192
	global_load_dwordx4 v[112:115], v[22:23], off offset:256
	global_load_dwordx4 v[116:119], v[22:23], off offset:320
	global_load_dwordx4 v[120:123], v[22:23], off offset:384
	global_load_dwordx4 v[124:127], v[22:23], off offset:448
	global_load_dwordx4 v[128:131], v[22:23], off offset:512
	global_load_dwordx4 v[132:135], v[22:23], off offset:576
	global_load_dwordx4 v[136:139], v[22:23], off offset:640
	global_load_dwordx4 v[140:143], v[22:23], off offset:704
	global_load_dwordx4 v[144:147], v[22:23], off offset:768
	global_load_dwordx4 v[148:151], v[22:23], off offset:832
	global_load_dwordx4 v[152:155], v[22:23], off offset:896
	global_load_dwordx4 v[156:159], v[22:23], off offset:960
	s_addc_u32 s17, s17, 0
	s_cmpk_eq_i32 s16, 0x1000
	s_waitcnt vmcnt(15)
	v_mfma_f32_16x16x32_bf16 v[0:3], v[30:33], v[96:99], v[0:3]
	s_waitcnt vmcnt(14)
	v_mfma_f32_16x16x32_bf16 v[0:3], v[34:37], v[100:103], v[0:3]
	s_waitcnt vmcnt(13)
	v_mfma_f32_16x16x32_bf16 v[0:3], v[38:41], v[104:107], v[0:3]
	s_waitcnt vmcnt(12)
	v_mfma_f32_16x16x32_bf16 v[0:3], v[42:45], v[108:111], v[0:3]
	s_waitcnt vmcnt(11)
	v_mfma_f32_16x16x32_bf16 v[0:3], v[46:49], v[112:115], v[0:3]
	s_waitcnt vmcnt(10)
	v_mfma_f32_16x16x32_bf16 v[0:3], v[50:53], v[116:119], v[0:3]
	s_waitcnt vmcnt(9)
	v_mfma_f32_16x16x32_bf16 v[0:3], v[54:57], v[120:123], v[0:3]
	s_waitcnt vmcnt(8)
	v_mfma_f32_16x16x32_bf16 v[0:3], v[58:61], v[124:127], v[0:3]
	s_waitcnt vmcnt(7)
	v_mfma_f32_16x16x32_bf16 v[0:3], v[62:65], v[128:131], v[0:3]
	s_waitcnt vmcnt(6)
	v_mfma_f32_16x16x32_bf16 v[0:3], v[66:69], v[132:135], v[0:3]
	s_waitcnt vmcnt(5)
	v_mfma_f32_16x16x32_bf16 v[0:3], v[70:73], v[136:139], v[0:3]
	s_waitcnt vmcnt(4)
	v_mfma_f32_16x16x32_bf16 v[0:3], v[74:77], v[140:143], v[0:3]
	s_waitcnt vmcnt(3)
	v_mfma_f32_16x16x32_bf16 v[0:3], v[78:81], v[144:147], v[0:3]
	s_waitcnt vmcnt(2)
	v_mfma_f32_16x16x32_bf16 v[0:3], v[82:85], v[148:151], v[0:3]
	s_waitcnt vmcnt(1)
	v_mfma_f32_16x16x32_bf16 v[0:3], v[86:89], v[152:155], v[0:3]
	s_waitcnt vmcnt(0)
	v_mfma_f32_16x16x32_bf16 v[0:3], v[90:93], v[156:159], v[0:3]
	s_cbranch_scc0 .LBB0_178
	global_load_dword v8, v[10:11], off
	s_and_saveexec_b64 s[16:17], s[0:1]
	s_xor_b64 s[16:17], exec, s[16:17]
	s_cbranch_execz .LBB0_181
	s_waitcnt vmcnt(0)
	s_nop 1
	v_add_f32_e32 v4, v0, v8
	v_mul_f32_e64 v5, |v4|, s9
	v_exp_f32_e32 v15, v5
	v_add_f32_e32 v23, v1, v8
	v_min_f32_e32 v4, 0, v4
	v_add_f32_e32 v5, 1.0, v15
	v_add_f32_e32 v6, -1.0, v5
	v_sub_f32_e32 v7, v6, v5
	v_sub_f32_e32 v6, v15, v6
	v_add_f32_e32 v7, 1.0, v7
	v_frexp_mant_f32_e32 v21, v5
	v_add_f32_e32 v22, v6, v7
	v_cvt_f64_f32_e32 v[6:7], v5
	v_frexp_exp_i32_f64_e32 v6, v[6:7]
	v_cmp_gt_f32_e32 vcc, s11, v21
	s_nop 1
	v_subbrev_co_u32_e32 v21, vcc, 0, v6, vcc
	v_mul_f32_e64 v6, |v23|, s9
	v_exp_f32_e32 v29, v6
	v_sub_u32_e32 v7, 0, v21
	v_ldexp_f32 v6, v5, v7
	v_ldexp_f32 v22, v22, v7
	v_add_f32_e32 v7, 1.0, v29
	v_min_f32_e32 v5, 0, v23
	v_add_f32_e32 v23, -1.0, v7
	v_sub_f32_e32 v30, v23, v7
	v_add_f32_e32 v30, 1.0, v30
	v_sub_f32_e32 v23, v29, v23
	v_add_f32_e32 v23, v23, v30
	v_frexp_mant_f32_e32 v32, v7
	v_cvt_f64_f32_e32 v[30:31], v7
	v_frexp_exp_i32_f64_e32 v30, v[30:31]
	v_cmp_gt_f32_e32 vcc, s11, v32
	s_nop 1
	v_subbrev_co_u32_e32 v46, vcc, 0, v30, vcc
	v_sub_u32_e32 v30, 0, v46
	v_ldexp_f32 v7, v7, v30
	v_ldexp_f32 v23, v23, v30
	v_pk_add_f32 v[30:31], v[6:7], 1.0 op_sel_hi:[1,0]
	v_pk_add_f32 v[38:39], v[6:7], -1.0 op_sel_hi:[1,0]
	v_pk_add_f32 v[32:33], v[30:31], -1.0 op_sel_hi:[1,0]
	v_pk_add_f32 v[40:41], v[38:39], 1.0 op_sel_hi:[1,0]
	v_pk_add_f32 v[32:33], v[6:7], v[32:33] neg_lo:[0,1] neg_hi:[0,1]
	v_pk_add_f32 v[6:7], v[6:7], v[40:41] neg_lo:[0,1] neg_hi:[0,1]
	v_pk_add_f32 v[32:33], v[22:23], v[32:33]
	v_pk_add_f32 v[6:7], v[22:23], v[6:7]
	v_pk_add_f32 v[34:35], v[30:31], v[32:33]
	v_pk_add_f32 v[22:23], v[38:39], v[6:7]
	v_rcp_f32_e32 v36, v34
	v_rcp_f32_e32 v37, v35
	v_pk_add_f32 v[30:31], v[34:35], v[30:31] neg_lo:[0,1] neg_hi:[0,1]
	v_pk_add_f32 v[38:39], v[22:23], v[38:39] neg_lo:[0,1] neg_hi:[0,1]
	v_pk_add_f32 v[30:31], v[32:33], v[30:31] neg_lo:[0,1] neg_hi:[0,1]
	v_pk_mul_f32 v[32:33], v[22:23], v[36:37]
	v_pk_add_f32 v[6:7], v[6:7], v[38:39] neg_lo:[0,1] neg_hi:[0,1]
	v_pk_mul_f32 v[38:39], v[34:35], v[32:33]
; __device__ __forceinline__ float log_sigmoidf_(float x) { return fminf(x, 0.f) - log1pf(__expf(-fabsf(x))); }
; __device__ __forceinline__ void gates_phase(const bf16_t* HB, const bf16_t* WG16, const float* bg, float* LI, float* LF) {
;     ...
;             for (int j = 0; j < 4; ++j) o[j] = log_sigmoidf_(acc[j] + bias);
;             *(f32x4*)(LF + (size_t)(bb * 8 + g) * SEQ + s) = o; }
	v_cmp_neq_f32_e32 vcc, s13, v15
	v_pk_fma_f32 v[40:41], v[32:33], v[34:35], v[38:39] neg_lo:[0,0,1] neg_hi:[0,0,1]
	s_nop 0
	v_pk_fma_f32 v[40:41], v[32:33], v[30:31], v[40:41]
	s_nop 0
	v_pk_add_f32 v[42:43], v[38:39], v[40:41]
	s_nop 0
	v_pk_add_f32 v[44:45], v[22:23], v[42:43] neg_lo:[0,1] neg_hi:[0,1]
	v_pk_add_f32 v[38:39], v[42:43], v[38:39] neg_lo:[0,1] neg_hi:[0,1]
	v_pk_add_f32 v[22:23], v[22:23], v[44:45] neg_lo:[0,1] neg_hi:[0,1]
	s_nop 0
	v_pk_add_f32 v[22:23], v[22:23], v[42:43] neg_lo:[0,1] neg_hi:[0,1]
	s_nop 0
	v_pk_add_f32 v[6:7], v[6:7], v[22:23]
	v_pk_add_f32 v[22:23], v[38:39], v[40:41] neg_lo:[0,1] neg_hi:[0,1]
	s_nop 0
	v_pk_add_f32 v[6:7], v[22:23], v[6:7]
	s_nop 0
	v_pk_add_f32 v[22:23], v[44:45], v[6:7]
	s_nop 0
	v_pk_mul_f32 v[38:39], v[36:37], v[22:23]
	s_nop 0
	v_pk_mul_f32 v[40:41], v[34:35], v[38:39]
	s_nop 0
	v_pk_fma_f32 v[34:35], v[38:39], v[34:35], v[40:41] neg_lo:[0,0,1] neg_hi:[0,0,1]
	s_nop 0
	v_pk_fma_f32 v[30:31], v[38:39], v[30:31], v[34:35]
	v_pk_add_f32 v[34:35], v[44:45], v[22:23] neg_lo:[0,1] neg_hi:[0,1]
	s_nop 0
	v_pk_add_f32 v[6:7], v[6:7], v[34:35]
	v_pk_add_f32 v[34:35], v[40:41], v[30:31]
	s_nop 0
	v_pk_add_f32 v[42:43], v[22:23], v[34:35] neg_lo:[0,1] neg_hi:[0,1]
	v_pk_add_f32 v[40:41], v[34:35], v[40:41] neg_lo:[0,1] neg_hi:[0,1]
	v_pk_add_f32 v[22:23], v[22:23], v[42:43] neg_lo:[0,1] neg_hi:[0,1]
	s_nop 0
	v_pk_add_f32 v[22:23], v[22:23], v[34:35] neg_lo:[0,1] neg_hi:[0,1]
	s_nop 0
	v_pk_add_f32 v[6:7], v[6:7], v[22:23]
	v_pk_add_f32 v[22:23], v[40:41], v[30:31] neg_lo:[0,1] neg_hi:[0,1]
	s_nop 0
	v_pk_add_f32 v[6:7], v[22:23], v[6:7]
	v_pk_add_f32 v[22:23], v[32:33], v[38:39]
	v_pk_add_f32 v[6:7], v[42:43], v[6:7]
	v_pk_add_f32 v[30:31], v[22:23], v[32:33] neg_lo:[0,1] neg_hi:[0,1]
	v_pk_mul_f32 v[6:7], v[36:37], v[6:7]
	v_pk_add_f32 v[30:31], v[38:39], v[30:31] neg_lo:[0,1] neg_hi:[0,1]
	v_cvt_f32_i32_e32 v37, v46
	v_pk_add_f32 v[6:7], v[30:31], v[6:7]
	v_cvt_f32_i32_e32 v36, v21
	v_pk_add_f32 v[30:31], v[22:23], v[6:7]
	v_add_f32_e32 v21, v2, v8
	v_pk_mul_f32 v[32:33], v[30:31], v[30:31]
	v_pk_add_f32 v[22:23], v[30:31], v[22:23] neg_lo:[0,1] neg_hi:[0,1]
	v_pk_fma_f32 v[34:35], v[32:33], s[8:9], v[18:19] op_sel_hi:[1,0,0]
	v_pk_add_f32 v[6:7], v[6:7], v[22:23] neg_lo:[0,1] neg_hi:[0,1]
	v_ldexp_f32 v22, v30, 1
	v_pk_fma_f32 v[34:35], v[32:33], v[34:35], s[10:11] op_sel_hi:[1,1,0]
	v_ldexp_f32 v23, v31, 1
	v_pk_mul_f32 v[30:31], v[30:31], v[32:33]
	v_pk_mul_f32 v[32:33], v[36:37], s[12:13] op_sel_hi:[1,0]
	v_pk_mul_f32 v[30:31], v[30:31], v[34:35]
	v_pk_fma_f32 v[40:41], v[36:37], s[12:13], v[32:33] op_sel_hi:[1,0,1] neg_lo:[0,0,1] neg_hi:[0,0,1]
	v_pk_add_f32 v[34:35], v[22:23], v[30:31]
	v_ldexp_f32 v39, v7, 1
	v_pk_add_f32 v[22:23], v[34:35], v[22:23] neg_lo:[0,1] neg_hi:[0,1]
	v_pk_fma_f32 v[36:37], v[36:37], s[14:15], v[40:41] op_sel_hi:[1,0,1]
	v_pk_add_f32 v[22:23], v[30:31], v[22:23] neg_lo:[0,1] neg_hi:[0,1]
	v_ldexp_f32 v6, v6, 1
	v_mov_b32_e32 v30, v32
	v_mov_b32_e32 v31, v23
	v_mov_b32_e32 v38, v36
	v_mov_b32_e32 v7, v39
	v_pk_add_f32 v[30:31], v[30:31], v[38:39]
	v_pk_add_f32 v[38:39], v[6:7], v[22:23]
	v_mov_b32_e32 v23, v35
	v_mov_b32_e32 v7, v39
	v_pk_add_f32 v[40:41], v[32:33], v[36:37]
	v_pk_add_f32 v[6:7], v[6:7], v[22:23]
	v_pk_add_f32 v[22:23], v[34:35], v[38:39]
	v_mov_b32_e32 v50, v34
	v_pk_add_f32 v[42:43], v[40:41], v[22:23]
	v_mov_b32_e32 v48, v22
	v_mov_b32_e32 v49, v43
	v_mov_b32_e32 v51, v41
	v_pk_add_f32 v[48:49], v[48:49], v[50:51] neg_lo:[0,1] neg_hi:[0,1]
	v_mov_b32_e32 v44, v42
	v_mov_b32_e32 v45, v41
	v_mov_b32_e32 v46, v40
	v_mov_b32_e32 v47, v33
	v_mov_b32_e32 v50, v40
	v_mov_b32_e32 v51, v43
	v_mov_b32_e32 v33, v49
	v_pk_add_f32 v[44:45], v[44:45], v[46:47] neg_lo:[0,1] neg_hi:[0,1]
	v_mov_b32_e32 v46, v22
	v_mov_b32_e32 v47, v37
	v_pk_add_f32 v[32:33], v[50:51], v[32:33] neg_lo:[0,1] neg_hi:[0,1]
	v_pk_add_f32 v[46:47], v[46:47], v[44:45] neg_lo:[0,1] neg_hi:[0,1]
	v_mov_b32_e32 v50, v32
	v_mov_b32_e32 v51, v45
	v_mov_b32_e32 v52, v42
	v_mov_b32_e32 v53, v23
	v_mov_b32_e32 v45, v35
	v_pk_add_f32 v[50:51], v[36:37], v[50:51] neg_lo:[0,1] neg_hi:[0,1]
	v_pk_add_f32 v[44:45], v[52:53], v[44:45] neg_lo:[0,1] neg_hi:[0,1]
	v_mov_b32_e32 v37, v41
	v_pk_add_f32 v[30:31], v[30:31], v[44:45] neg_lo:[0,1] neg_hi:[0,1]
	v_pk_add_f32 v[32:33], v[36:37], v[32:33] neg_lo:[0,1] neg_hi:[0,1]
	v_pk_add_f32 v[6:7], v[6:7], v[48:49] neg_lo:[0,1] neg_hi:[0,1]
	v_pk_add_f32 v[22:23], v[22:23], v[34:35] neg_lo:[0,1] neg_hi:[0,1]
	v_pk_add_f32 v[34:35], v[6:7], v[32:33]
	v_mov_b32_e32 v33, v47
	v_mov_b32_e32 v7, v31
	v_pk_add_f32 v[36:37], v[46:47], v[30:31]
	v_pk_add_f32 v[6:7], v[32:33], v[6:7]
	v_mov_b32_e32 v30, v34
	v_pk_add_f32 v[6:7], v[6:7], v[50:51] neg_lo:[0,1] neg_hi:[0,1]
	v_mov_b32_e32 v31, v37
	v_pk_add_f32 v[22:23], v[38:39], v[22:23] neg_lo:[0,1] neg_hi:[0,1]
	v_pk_add_f32 v[30:31], v[30:31], v[6:7] neg_lo:[0,1] neg_hi:[0,1]
	v_pk_add_f32 v[6:7], v[22:23], v[6:7] neg_lo:[0,1] neg_hi:[0,1]
	v_pk_add_f32 v[30:31], v[32:33], v[30:31] neg_lo:[0,1] neg_hi:[0,1]
	v_pk_add_f32 v[22:23], v[36:37], v[34:35]
	v_pk_add_f32 v[6:7], v[6:7], v[30:31]
	v_pk_add_f32 v[30:31], v[42:43], v[22:23]
	s_nop 0
	v_pk_add_f32 v[32:33], v[30:31], v[42:43] neg_lo:[0,1] neg_hi:[0,1]
	s_nop 0
	v_pk_add_f32 v[22:23], v[22:23], v[32:33] neg_lo:[0,1] neg_hi:[0,1]
	s_nop 0
	v_pk_add_f32 v[6:7], v[6:7], v[22:23]
	v_mul_f32_e64 v22, |v21|, s9
	v_pk_add_f32 v[6:7], v[30:31], v[6:7]
	s_nop 0
	v_cndmask_b32_e32 v6, v26, v6, vcc
	v_cmp_neq_f32_e32 vcc, s13, v29
	s_nop 1
	v_cndmask_b32_e32 v7, v26, v7, vcc
	v_cmp_ngt_f32_e32 vcc, -1.0, v29
	s_nop 1
	v_cndmask_b32_e32 v7, v27, v7, vcc
; __device__ __forceinline__ float log_sigmoidf_(float x) { return fminf(x, 0.f) - log1pf(__expf(-fabsf(x))); }
; __device__ __forceinline__ void gates_phase(const bf16_t* HB, const bf16_t* WG16, const float* bg, float* LI, float* LF) {
;     ...
;             for (int j = 0; j < 4; ++j) o[j] = log_sigmoidf_(acc[j] + bias);
;             *(f32x4*)(LF + (size_t)(bb * 8 + g) * SEQ + s) = o; }
	v_cmp_ngt_f32_e32 vcc, -1.0, v15
	s_nop 1
	v_cndmask_b32_e32 v6, v27, v6, vcc
	v_cmp_neq_f32_e32 vcc, -1.0, v15
	s_nop 1
	v_cndmask_b32_e32 v6, v28, v6, vcc
	v_cmp_neq_f32_e32 vcc, -1.0, v29
	s_nop 1
	v_cndmask_b32_e32 v7, v28, v7, vcc
	v_cmp_lt_f32_e64 vcc, |v29|, s15
	s_nop 1
	v_cndmask_b32_e32 v7, v7, v29, vcc
	v_exp_f32_e32 v29, v22
	v_cmp_lt_f32_e64 vcc, |v15|, s15
	s_nop 1
	v_cndmask_b32_e32 v6, v6, v15, vcc
	v_pk_add_f32 v[4:5], v[4:5], v[6:7] neg_lo:[0,1] neg_hi:[0,1]
	v_add_f32_e32 v7, 1.0, v29
	v_add_f32_e32 v15, -1.0, v7
	v_min_f32_e32 v6, 0, v21
	v_sub_f32_e32 v21, v15, v7
	v_add_f32_e32 v21, 1.0, v21
	v_sub_f32_e32 v15, v29, v15
	v_add_f32_e32 v15, v15, v21
	v_frexp_mant_f32_e32 v21, v7
	v_cvt_f64_f32_e32 v[22:23], v7
	v_frexp_exp_i32_f64_e32 v22, v[22:23]
	v_cmp_gt_f32_e32 vcc, s11, v21
	s_nop 1
	v_subbrev_co_u32_e32 v21, vcc, 0, v22, vcc
	v_sub_u32_e32 v22, 0, v21
	v_ldexp_f32 v7, v7, v22
	v_ldexp_f32 v15, v15, v22
	v_add_f32_e32 v22, -1.0, v7
	v_add_f32_e32 v23, 1.0, v22
	v_sub_f32_e32 v23, v7, v23
	v_add_f32_e32 v30, v15, v23
	v_add_f32_e32 v23, 1.0, v7
	v_add_f32_e32 v31, -1.0, v23
	v_sub_f32_e32 v7, v7, v31
	v_add_f32_e32 v7, v15, v7
	v_add_f32_e32 v15, v23, v7
	v_rcp_f32_e32 v36, v15
	v_sub_f32_e32 v23, v15, v23
	v_sub_f32_e32 v7, v7, v23
	v_add_f32_e32 v23, v22, v30
	v_sub_f32_e32 v22, v23, v22
	v_mul_f32_e32 v38, v23, v36
	v_sub_f32_e32 v37, v30, v22
	v_mul_f32_e32 v30, v15, v38
	v_fma_f32 v32, v38, v15, -v30
	v_fmac_f32_e32 v32, v38, v7
	v_add_f32_e32 v22, v30, v32
	v_sub_f32_e32 v31, v23, v22
	v_pk_add_f32 v[34:35], v[22:23], v[30:31] neg_lo:[0,1] neg_hi:[0,1]
	v_mov_b32_e32 v33, v22
	v_pk_add_f32 v[22:23], v[34:35], v[32:33] neg_lo:[0,1] neg_hi:[0,1]
	s_nop 0
	v_add_f32_e32 v23, v37, v23
	v_add_f32_e32 v22, v22, v23
	v_add_f32_e32 v23, v31, v22
	v_mul_f32_e32 v37, v36, v23
	v_mul_f32_e32 v30, v15, v37
	v_fma_f32 v32, v37, v15, -v30
	v_fmac_f32_e32 v32, v37, v7
	v_sub_f32_e32 v7, v31, v23
	v_add_f32_e32 v7, v22, v7
	v_add_f32_e32 v22, v30, v32
	v_sub_f32_e32 v31, v23, v22
	v_pk_add_f32 v[34:35], v[22:23], v[30:31] neg_lo:[0,1] neg_hi:[0,1]
	v_mov_b32_e32 v33, v22
	v_pk_add_f32 v[22:23], v[34:35], v[32:33] neg_lo:[0,1] neg_hi:[0,1]
	v_add_f32_e32 v15, v38, v37
	v_add_f32_e32 v7, v7, v23
	v_add_f32_e32 v7, v22, v7
	v_add_f32_e32 v7, v31, v7
	v_sub_f32_e32 v22, v15, v38
	v_mul_f32_e32 v7, v36, v7
	v_sub_f32_e32 v22, v37, v22
	v_add_f32_e32 v7, v22, v7
	v_add_f32_e32 v30, v15, v7
	v_mul_f32_e32 v31, v30, v30
	v_fmamk_f32 v22, v31, 0x3e9b6dac, v18
	v_fmaak_f32 v32, v31, v22, 0x3f2aaada
	v_cvt_f32_i32_e32 v22, v21
	v_sub_f32_e32 v15, v30, v15
	v_sub_f32_e32 v7, v7, v15
	v_mul_f32_e32 v15, v30, v31
	v_ldexp_f32 v23, v30, 1
	v_mul_f32_e32 v21, v15, v32
	v_pk_add_f32 v[32:33], v[22:23], v[20:21]
	v_pk_mul_f32 v[30:31], v[22:23], v[20:21]
	v_sub_f32_e32 v15, v33, v23
	v_ldexp_f32 v7, v7, 1
	v_fma_f32 v34, v22, s12, -v30
	v_sub_f32_e32 v15, v21, v15
	v_mov_b32_e32 v31, v33
	v_fmac_f32_e32 v34, 0xb102e308, v22
	v_add_f32_e32 v35, v7, v15
	v_pk_add_f32 v[22:23], v[30:31], v[34:35]
	v_add_f32_e32 v7, v3, v8
	v_pk_add_f32 v[36:37], v[22:23], v[22:23] op_sel:[0,1] op_sel_hi:[1,0]
	v_mov_b32_e32 v38, v22
	v_mov_b32_e32 v39, v36
	v_mov_b32_e32 v31, v22
	v_pk_add_f32 v[30:31], v[38:39], v[30:31] neg_lo:[0,1] neg_hi:[0,1]
	v_pk_mov_b32 v[38:39], v[22:23], v[36:37] op_sel:[1,0]
	v_mov_b32_e32 v32, v33
	v_mov_b32_e32 v33, v31
	v_mul_f32_e64 v8, |v7|, s9
	v_pk_add_f32 v[32:33], v[38:39], v[32:33] neg_lo:[0,1] neg_hi:[0,1]
	v_mov_b32_e32 v38, v35
	v_mov_b32_e32 v39, v22
	v_mov_b32_e32 v35, v23
	v_exp_f32_e32 v15, v8
	v_pk_add_f32 v[32:33], v[38:39], v[32:33] neg_lo:[0,1] neg_hi:[0,1]
	v_pk_add_f32 v[22:23], v[34:35], v[30:31] neg_lo:[0,1] neg_hi:[0,1]
	v_min_f32_e32 v7, 0, v7
	v_pk_add_f32 v[30:31], v[22:23], v[32:33]
	v_add_f32_e32 v8, 1.0, v15
	v_pk_add_f32 v[34:35], v[30:31], v[22:23] neg_lo:[0,1] neg_hi:[0,1]
	v_add_f32_e32 v21, -1.0, v8
	v_pk_add_f32 v[38:39], v[30:31], v[34:35] neg_lo:[0,1] neg_hi:[0,1]
	v_pk_add_f32 v[32:33], v[32:33], v[34:35] neg_lo:[0,1] neg_hi:[0,1]
	v_pk_add_f32 v[22:23], v[22:23], v[38:39] neg_lo:[0,1] neg_hi:[0,1]
	v_cvt_f64_f32_e32 v[34:35], v8
	v_sub_f32_e32 v23, v21, v8
	v_add_f32_e32 v23, 1.0, v23
	v_sub_f32_e32 v21, v15, v21
	v_add_f32_e32 v21, v21, v23
	v_frexp_mant_f32_e32 v23, v8
	v_frexp_exp_i32_f64_e32 v33, v[34:35]
	v_cmp_gt_f32_e32 vcc, s11, v23
	v_pk_add_f32 v[30:31], v[30:31], v[30:31] op_sel:[0,1] op_sel_hi:[1,0]
; __device__ __forceinline__ float log_sigmoidf_(float x) { return fminf(x, 0.f) - log1pf(__expf(-fabsf(x))); }
; __device__ __forceinline__ void gates_phase(const bf16_t* HB, const bf16_t* WG16, const float* bg, float* LI, float* LF) {
;     ...
;             for (int j = 0; j < 4; ++j) o[j] = log_sigmoidf_(acc[j] + bias);
;             *(f32x4*)(LF + (size_t)(bb * 8 + g) * SEQ + s) = o; }
	s_nop 0
	v_subbrev_co_u32_e32 v23, vcc, 0, v33, vcc
	v_sub_u32_e32 v33, 0, v23
	v_ldexp_f32 v8, v8, v33
	v_ldexp_f32 v21, v21, v33
	v_add_f32_e32 v33, -1.0, v8
	v_add_f32_e32 v35, 1.0, v8
	v_add_f32_e32 v34, 1.0, v33
	v_add_f32_e32 v38, -1.0, v35
	v_sub_f32_e32 v34, v8, v34
	v_sub_f32_e32 v8, v8, v38
	v_add_f32_e32 v8, v21, v8
	v_add_f32_e32 v34, v21, v34
	v_add_f32_e32 v21, v35, v8
	v_rcp_f32_e32 v44, v21
	v_sub_f32_e32 v35, v21, v35
	v_sub_f32_e32 v8, v8, v35
	v_add_f32_e32 v35, v33, v34
	v_mul_f32_e32 v45, v35, v44
	v_mul_f32_e32 v38, v21, v45
	v_fma_f32 v40, v45, v21, -v38
	v_sub_f32_e32 v33, v35, v33
	v_fmac_f32_e32 v40, v45, v8
	v_sub_f32_e32 v33, v34, v33
	v_add_f32_e32 v34, v38, v40
	v_sub_f32_e32 v39, v35, v34
	v_pk_add_f32 v[42:43], v[34:35], v[38:39] neg_lo:[0,1] neg_hi:[0,1]
	v_mov_b32_e32 v41, v34
	v_pk_add_f32 v[34:35], v[42:43], v[40:41] neg_lo:[0,1] neg_hi:[0,1]
	v_cmp_neq_f32_e32 vcc, s13, v29
	v_add_f32_e32 v33, v33, v35
	v_add_f32_e32 v33, v34, v33
	v_add_f32_e32 v35, v39, v33
	v_mul_f32_e32 v46, v44, v35
	v_mul_f32_e32 v38, v21, v46
	v_fma_f32 v40, v46, v21, -v38
	v_fmac_f32_e32 v40, v46, v8
	v_add_f32_e32 v34, v38, v40
	v_sub_f32_e32 v8, v39, v35
	v_sub_f32_e32 v39, v35, v34
	v_pk_add_f32 v[42:43], v[34:35], v[38:39] neg_lo:[0,1] neg_hi:[0,1]
	v_mov_b32_e32 v41, v34
	v_add_f32_e32 v8, v33, v8
	v_pk_add_f32 v[34:35], v[42:43], v[40:41] neg_lo:[0,1] neg_hi:[0,1]
	v_add_f32_e32 v33, v45, v46
	v_add_f32_e32 v8, v8, v35
	v_add_f32_e32 v8, v34, v8
	v_add_f32_e32 v8, v39, v8
	v_sub_f32_e32 v21, v33, v45
	v_mul_f32_e32 v8, v44, v8
	v_sub_f32_e32 v21, v46, v21
	v_add_f32_e32 v8, v21, v8
	v_add_f32_e32 v35, v33, v8
	v_cvt_f32_i32_e32 v34, v23
	v_mul_f32_e32 v38, v35, v35
	v_fmamk_f32 v21, v38, 0x3e9b6dac, v18
	v_fmaak_f32 v21, v38, v21, 0x3f2aaada
	v_sub_f32_e32 v23, v35, v33
	v_ldexp_f32 v39, v35, 1
	v_mul_f32_e32 v35, v35, v38
	v_pk_mul_f32 v[40:41], v[34:35], v[20:21]
	v_sub_f32_e32 v8, v8, v23
	v_fma_f32 v38, v34, s12, -v40
	v_fmac_f32_e32 v38, 0xb102e308, v34
	v_pk_add_f32 v[34:35], v[40:41], v[38:39]
	v_ldexp_f32 v8, v8, 1
	v_sub_f32_e32 v21, v35, v39
	v_sub_f32_e32 v21, v41, v21
	v_add_f32_e32 v43, v8, v21
	v_mov_b32_e32 v42, v40
	v_pk_add_f32 v[40:41], v[34:35], v[40:41] neg_lo:[0,1] neg_hi:[0,1]
	v_pk_add_f32 v[44:45], v[34:35], v[42:43]
	v_mov_b32_e32 v39, v34
	v_mov_b32_e32 v41, v45
	v_pk_add_f32 v[46:47], v[38:39], v[40:41] neg_lo:[0,1] neg_hi:[0,1]
	v_pk_add_f32 v[38:39], v[38:39], v[40:41]
	v_mov_b32_e32 v42, v43
	v_pk_add_f32 v[40:41], v[38:39], v[34:35] op_sel:[1,0] op_sel_hi:[0,1] neg_lo:[0,1] neg_hi:[0,1]
	v_pk_add_f32 v[48:49], v[44:45], v[40:41] op_sel_hi:[1,0] neg_lo:[0,1] neg_hi:[0,1]
	v_mov_b32_e32 v38, v45
	v_pk_mov_b32 v[40:41], v[34:35], v[40:41] op_sel:[1,0]
	v_mov_b32_e32 v43, v34
	v_pk_add_f32 v[40:41], v[38:39], v[40:41] neg_lo:[0,1] neg_hi:[0,1]
	v_mov_b32_e32 v48, v46
	v_pk_add_f32 v[34:35], v[42:43], v[40:41] neg_lo:[0,1] neg_hi:[0,1]
	v_pk_add_f32 v[42:43], v[36:37], v[30:31]
	v_pk_add_f32 v[40:41], v[48:49], v[34:35]
	v_pk_add_f32 v[36:37], v[42:43], v[36:37] neg_lo:[0,1] neg_hi:[0,1]
	v_mov_b32_e32 v33, v40
	v_pk_add_f32 v[30:31], v[30:31], v[36:37] neg_lo:[0,1] neg_hi:[0,1]
	v_mov_b32_e32 v23, v41
	v_pk_add_f32 v[22:23], v[32:33], v[22:23]
	v_mov_b32_e32 v31, v39
	v_pk_add_f32 v[30:31], v[30:31], v[22:23]
	v_mov_b32_e32 v47, v39
	v_mov_b32_e32 v41, v31
	v_pk_add_f32 v[32:33], v[40:41], v[46:47] neg_lo:[0,1] neg_hi:[0,1]
	v_mov_b32_e32 v35, v23
	v_sub_f32_e32 v8, v40, v32
	v_pk_add_f32 v[22:23], v[34:35], v[32:33] neg_lo:[0,1] neg_hi:[0,1]
	v_sub_f32_e32 v8, v46, v8
	v_add_f32_e32 v8, v22, v8
	v_pk_add_f32 v[22:23], v[8:9], v[22:23] op_sel_hi:[0,1]
	v_mov_b32_e32 v43, v23
	v_pk_add_f32 v[22:23], v[30:31], v[42:43]
	s_nop 0
	v_cndmask_b32_e32 v8, v26, v22, vcc
	v_cmp_neq_f32_e32 vcc, s13, v15
	s_nop 1
	v_cndmask_b32_e32 v21, v26, v23, vcc
	v_cmp_ngt_f32_e32 vcc, -1.0, v15
	s_nop 1
	v_cndmask_b32_e32 v21, v27, v21, vcc
	v_cmp_ngt_f32_e32 vcc, -1.0, v29
	s_nop 1
	v_cndmask_b32_e32 v8, v27, v8, vcc
	v_cmp_neq_f32_e32 vcc, -1.0, v29
	s_nop 1
	v_cndmask_b32_e32 v8, v28, v8, vcc
	v_cmp_neq_f32_e32 vcc, -1.0, v15
	s_nop 1
	v_cndmask_b32_e32 v21, v28, v21, vcc
	v_cmp_lt_f32_e64 vcc, |v15|, s15
	s_nop 1
	v_cndmask_b32_e32 v23, v21, v15, vcc
	v_cmp_lt_f32_e64 vcc, |v29|, s15
	s_nop 1
	v_cndmask_b32_e32 v22, v8, v29, vcc
	v_pk_add_f32 v[6:7], v[6:7], v[22:23] neg_lo:[0,1] neg_hi:[0,1]
